# GEMM main loops: all in-loop LDS-DMAs use scalar-base form (no 64-bit VALU address adds in the load segments); rest of hipcc 8-barrier loop unchanged
# baseline (speedup 1.0000x reference)
; #define PG8_STAGE(bufoff, gbase, voff) do { _Pragma("unroll") for (int _i = 0; _i < 2; ++_i) \
;         __builtin_amdgcn_global_load_lds((const unsigned*)((const char*)(gbase) + (voff)[_i]), (PG8_LAS unsigned*)(lds + (bufoff) + ldsw + _i * 8192), 16, 0, 0); } while (0)
; #define PG8_LDA(dst, b, h) do { _Pragma("unroll") for (int m = 0; m < 4; ++m) _Pragma("unroll") for (int k = 0; k < 2; ++k) dst[m][k] = *(const PG8_LAS bf16x8*)(lds + PG8_SA(b, h) + aoff + m * 2048 + k * 1024); } while (0)
; #define PG8_LDB(dst, b, h) do { _Pragma("unroll") for (int n = 0; n < 2; ++n) _Pragma("unroll") for (int k = 0; k < 2; ++k) dst[n][k] = *(const PG8_LAS bf16x8*)(lds + PG8_SB(b, h) + boff + n * 2048 + k * 1024); } while (0)
; #define PG8_WAIT_V(n) asm volatile("s_waitcnt vmcnt(" #n ")" ::: "memory")
; template <class Epi, class Sched, bool ALIGN_EPI = false, bool SP2 = false>
; __device__ __forceinline__ void gemm_phase(PG8_LAS unsigned char* lds, const Gemm g, const Sched& S, const Epi& E) {
;     ...
;             const char* a1 = cA + (size_t)(t + 1) * kstep;
;             const char* a2 = last ? nA : cA + (size_t)(t + 2) * kstep; const char* b2 = last ? nB : cB + (size_t)(t + 2) * kstep;
;             const char* a3 = a2 + kstep; const char* b3 = b2 + kstep;
;             if (last && has_next) S.a_ready(nxt);
;             if constexpr (SP2) {
;             PG8_LDB(B0, 0, 0); PG8_LDB(B1, 0, 1); PG8_SCHED; PG8_LDA(At, 0, 0); PG8_STAGE(PG8_SA(1, 1), a1 + hstep, voffA);
;             PG8_WAIT_V(8); PG8_WAIT_L(0); PG8_BAR; PG8_MMA(0, 0, At, B0); PG8_MMA(0, 1, At, B1); PG8_BAR; PG8_SCHED;
;             PG8_LDA(At, 0, 1); PG8_STAGE(PG8_SB(0, 0), b2, voffB); PG8_STAGE(PG8_SB(0, 1), b2 + hstep, voffB); PG8_STAGE(PG8_SA(0, 0), a2, voffA);
;             PG8_WAIT_V(8); PG8_WAIT_L(0); PG8_BAR; PG8_MMA(1, 0, At, B0); PG8_MMA(1, 1, At, B1); PG8_BAR; PG8_SCHED;
;             PG8_LDB(B0, 1, 0); PG8_LDB(B1, 1, 1); PG8_SCHED; PG8_LDA(At, 1, 0); PG8_STAGE(PG8_SA(0, 1), a2 + hstep, voffA);
;             PG8_WAIT_V(8); PG8_WAIT_L(0); PG8_BAR; PG8_MMA(0, 0, At, B0); PG8_MMA(0, 1, At, B1); PG8_BAR; PG8_SCHED;
;             PG8_LDA(At, 1, 1); PG8_STAGE(PG8_SB(1, 0), b3, voffB); PG8_STAGE(PG8_SB(1, 1), b3 + hstep, voffB); PG8_STAGE(PG8_SA(1, 0), a3, voffA);
;             PG8_WAIT_V(8); PG8_WAIT_L(0); PG8_BAR; PG8_MMA(1, 0, At, B0); PG8_MMA(1, 1, At, B1); PG8_BAR; PG8_SCHED;
.LBB0_203:
	ds_read_b128 v[150:153], v161
	ds_read_b128 v[154:157], v161 offset:1024
	ds_read_b128 v[166:169], v161 offset:2048
	ds_read_b128 v[170:173], v161 offset:3072
	ds_read_b128 v[174:177], v162
	ds_read_b128 v[178:181], v162 offset:1024
	ds_read_b128 v[182:185], v162 offset:2048
	ds_read_b128 v[186:189], v162 offset:3072
	s_add_u32 s30, s28, 0xfff80080
	s_addc_u32 s31, s29, -1
	s_cmp_eq_u32 s83, 28
	s_cselect_b32 s35, s6, s31
	s_cselect_b32 s34, s23, s30
	s_cselect_b32 s31, s21, s82
	s_cselect_b32 s30, s70, s71
	s_add_i32 m0, s39, 0xc000
	ds_read_b128 v[190:193], v163
	ds_read_b128 v[194:197], v163 offset:1024
	ds_read_b128 v[198:201], v163 offset:2048
	ds_read_b128 v[206:209], v163 offset:3072
	ds_read_b128 v[210:213], v163 offset:4096
	ds_read_b128 v[214:217], v163 offset:5120
	ds_read_b128 v[218:221], v163 offset:6144
	ds_read_b128 v[222:225], v163 offset:7168
	global_load_lds_dwordx4 v142, s[28:29]
	s_add_i32 m0, s39, 0xe000
	s_nop 0
	global_load_lds_dwordx4 v144, s[28:29]
	s_waitcnt vmcnt(8)
	s_waitcnt lgkmcnt(0)
	s_barrier
	s_setprio 1
	s_waitcnt lgkmcnt(0)
	v_mfma_f32_16x16x32_bf16 v[126:129], v[150:153], v[190:193], v[126:129]
	v_mfma_f32_16x16x32_bf16 v[122:125], v[166:169], v[190:193], v[122:125]
	v_mfma_f32_16x16x32_bf16 v[110:113], v[150:153], v[198:201], v[110:113]
	v_mfma_f32_16x16x32_bf16 v[106:109], v[166:169], v[198:201], v[106:109]
	v_mfma_f32_16x16x32_bf16 v[94:97], v[150:153], v[210:213], v[94:97]
	v_mfma_f32_16x16x32_bf16 v[90:93], v[166:169], v[210:213], v[90:93]
	v_mfma_f32_16x16x32_bf16 v[78:81], v[150:153], v[218:221], v[78:81]
	v_mfma_f32_16x16x32_bf16 v[74:77], v[166:169], v[218:221], v[74:77]
	v_mfma_f32_16x16x32_bf16 v[126:129], v[154:157], v[194:197], v[126:129]
	v_mfma_f32_16x16x32_bf16 v[122:125], v[170:173], v[194:197], v[122:125]
	v_mfma_f32_16x16x32_bf16 v[110:113], v[154:157], v[206:209], v[110:113]
	v_mfma_f32_16x16x32_bf16 v[106:109], v[170:173], v[206:209], v[106:109]
	v_mfma_f32_16x16x32_bf16 v[94:97], v[154:157], v[214:217], v[94:97]
	v_mfma_f32_16x16x32_bf16 v[90:93], v[170:173], v[214:217], v[90:93]
	v_mfma_f32_16x16x32_bf16 v[78:81], v[154:157], v[222:225], v[78:81]
	v_mfma_f32_16x16x32_bf16 v[74:77], v[170:173], v[222:225], v[74:77]
	s_setprio 0
	s_setprio 1
	v_mfma_f32_16x16x32_bf16 v[118:121], v[174:177], v[190:193], v[118:121]
	v_mfma_f32_16x16x32_bf16 v[114:117], v[182:185], v[190:193], v[114:117]
	v_mfma_f32_16x16x32_bf16 v[102:105], v[174:177], v[198:201], v[102:105]
	v_mfma_f32_16x16x32_bf16 v[98:101], v[182:185], v[198:201], v[98:101]
	v_mfma_f32_16x16x32_bf16 v[86:89], v[174:177], v[210:213], v[86:89]
	v_mfma_f32_16x16x32_bf16 v[82:85], v[182:185], v[210:213], v[82:85]
	v_mfma_f32_16x16x32_bf16 v[70:73], v[174:177], v[218:221], v[70:73]
	v_mfma_f32_16x16x32_bf16 v[66:69], v[182:185], v[218:221], v[66:69]
	v_mfma_f32_16x16x32_bf16 v[118:121], v[178:181], v[194:197], v[118:121]
	v_mfma_f32_16x16x32_bf16 v[114:117], v[186:189], v[194:197], v[114:117]
	v_mfma_f32_16x16x32_bf16 v[102:105], v[178:181], v[206:209], v[102:105]
	v_mfma_f32_16x16x32_bf16 v[98:101], v[186:189], v[206:209], v[98:101]
	v_mfma_f32_16x16x32_bf16 v[86:89], v[178:181], v[214:217], v[86:89]
	v_mfma_f32_16x16x32_bf16 v[82:85], v[186:189], v[214:217], v[82:85]
	v_mfma_f32_16x16x32_bf16 v[70:73], v[178:181], v[222:225], v[70:73]
	v_mfma_f32_16x16x32_bf16 v[66:69], v[186:189], v[222:225], v[66:69]
	s_setprio 0
	s_barrier
	s_add_i32 s84, s79, s36
	s_add_u32 s64, s30, 0x80
	s_addc_u32 s65, s31, 0
	s_mov_b32 m0, s84
	ds_read_b128 v[190:193], v163 offset:16384
	ds_read_b128 v[194:197], v163 offset:17408
	ds_read_b128 v[198:201], v163 offset:18432
	ds_read_b128 v[206:209], v163 offset:19456
	ds_read_b128 v[210:213], v163 offset:20480
	ds_read_b128 v[214:217], v163 offset:21504
	ds_read_b128 v[218:221], v163 offset:22528
	ds_read_b128 v[222:225], v163 offset:23552
	global_load_lds_dwordx4 v134, s[30:31]
	s_add_i32 m0, s84, 0x2000
	s_add_u32 s84, s30, 0x80000
	s_addc_u32 s85, s31, 0
	s_add_i32 s86, s80, s36
	global_load_lds_dwordx4 v138, s[30:31]
	s_mov_b32 m0, s86
	s_add_u32 s66, s34, 0x80
	s_addc_u32 s67, s35, 0
	global_load_lds_dwordx4 v134, s[84:85]
	s_add_i32 m0, s86, 0x2000
	s_nop 0
	global_load_lds_dwordx4 v138, s[84:85]
	s_mov_b32 m0, s39
	s_nop 0
	global_load_lds_dwordx4 v132, s[34:35]
	s_mov_b32 m0, s40
	s_nop 0
	global_load_lds_dwordx4 v136, s[34:35]
	s_waitcnt vmcnt(8)
	s_waitcnt lgkmcnt(0)
	s_barrier
	s_setprio 1
	s_waitcnt lgkmcnt(0)
	v_mfma_f32_16x16x32_bf16 v[62:65], v[150:153], v[190:193], v[62:65]
	v_mfma_f32_16x16x32_bf16 v[58:61], v[166:169], v[190:193], v[58:61]
	v_mfma_f32_16x16x32_bf16 v[46:49], v[150:153], v[198:201], v[46:49]
	v_mfma_f32_16x16x32_bf16 v[42:45], v[166:169], v[198:201], v[42:45]
	v_mfma_f32_16x16x32_bf16 v[30:33], v[150:153], v[210:213], v[30:33]
	v_mfma_f32_16x16x32_bf16 v[26:29], v[166:169], v[210:213], v[26:29]
	v_mfma_f32_16x16x32_bf16 v[14:17], v[150:153], v[218:221], v[14:17]
	v_mfma_f32_16x16x32_bf16 v[10:13], v[166:169], v[218:221], v[10:13]
	v_mfma_f32_16x16x32_bf16 v[62:65], v[154:157], v[194:197], v[62:65]
	v_mfma_f32_16x16x32_bf16 v[58:61], v[170:173], v[194:197], v[58:61]
	v_mfma_f32_16x16x32_bf16 v[46:49], v[154:157], v[206:209], v[46:49]
	v_mfma_f32_16x16x32_bf16 v[42:45], v[170:173], v[206:209], v[42:45]
	v_mfma_f32_16x16x32_bf16 v[30:33], v[154:157], v[214:217], v[30:33]
	v_mfma_f32_16x16x32_bf16 v[26:29], v[170:173], v[214:217], v[26:29]
	v_mfma_f32_16x16x32_bf16 v[14:17], v[154:157], v[222:225], v[14:17]
	v_mfma_f32_16x16x32_bf16 v[10:13], v[170:173], v[222:225], v[10:13]
	s_setprio 0
	s_setprio 1
	v_mfma_f32_16x16x32_bf16 v[54:57], v[174:177], v[190:193], v[54:57]
	v_mfma_f32_16x16x32_bf16 v[50:53], v[182:185], v[190:193], v[50:53]
	v_mfma_f32_16x16x32_bf16 v[38:41], v[174:177], v[198:201], v[38:41]
	v_mfma_f32_16x16x32_bf16 v[34:37], v[182:185], v[198:201], v[34:37]
	v_mfma_f32_16x16x32_bf16 v[22:25], v[174:177], v[210:213], v[22:25]
	v_mfma_f32_16x16x32_bf16 v[18:21], v[182:185], v[210:213], v[18:21]
	v_mfma_f32_16x16x32_bf16 v[6:9], v[174:177], v[218:221], v[6:9]
	v_mfma_f32_16x16x32_bf16 v[2:5], v[182:185], v[218:221], v[2:5]
	v_mfma_f32_16x16x32_bf16 v[54:57], v[178:181], v[194:197], v[54:57]
	v_mfma_f32_16x16x32_bf16 v[50:53], v[186:189], v[194:197], v[50:53]
	v_mfma_f32_16x16x32_bf16 v[38:41], v[178:181], v[206:209], v[38:41]
	v_mfma_f32_16x16x32_bf16 v[34:37], v[186:189], v[206:209], v[34:37]
	v_mfma_f32_16x16x32_bf16 v[22:25], v[178:181], v[214:217], v[22:25]
	v_mfma_f32_16x16x32_bf16 v[18:21], v[186:189], v[214:217], v[18:21]
	v_mfma_f32_16x16x32_bf16 v[6:9], v[178:181], v[222:225], v[6:9]
	v_mfma_f32_16x16x32_bf16 v[2:5], v[186:189], v[222:225], v[2:5]
	s_setprio 0
	s_barrier
; #define PG8_STAGE(bufoff, gbase, voff) do { _Pragma("unroll") for (int _i = 0; _i < 2; ++_i) \
;         __builtin_amdgcn_global_load_lds((const unsigned*)((const char*)(gbase) + (voff)[_i]), (PG8_LAS unsigned*)(lds + (bufoff) + ldsw + _i * 8192), 16, 0, 0); } while (0)
; #define PG8_LDA(dst, b, h) do { _Pragma("unroll") for (int m = 0; m < 4; ++m) _Pragma("unroll") for (int k = 0; k < 2; ++k) dst[m][k] = *(const PG8_LAS bf16x8*)(lds + PG8_SA(b, h) + aoff + m * 2048 + k * 1024); } while (0)
; #define PG8_LDB(dst, b, h) do { _Pragma("unroll") for (int n = 0; n < 2; ++n) _Pragma("unroll") for (int k = 0; k < 2; ++k) dst[n][k] = *(const PG8_LAS bf16x8*)(lds + PG8_SB(b, h) + boff + n * 2048 + k * 1024); } while (0)
; #define PG8_MMA(ai, bj, At, Bt) do { __builtin_amdgcn_s_setprio(1); _Pragma("unroll") for (int m = 0; m < 4; ++m) _Pragma("unroll") for (int n = 0; n < 2; ++n) _Pragma("unroll") for (int k = 0; k < 2; ++k) \
;         acc[ai][bj][m][n] = __builtin_amdgcn_mfma_f32_16x16x32_bf16(Bt[n][k], At[m][k], acc[ai][bj][m][n], 0, 0, 0); __builtin_amdgcn_s_setprio(0); } while (0)
; #define PG8_WAIT_V(n) asm volatile("s_waitcnt vmcnt(" #n ")" ::: "memory")
; #define PG8_WAIT_L(n) asm volatile("s_waitcnt lgkmcnt(" #n ")" ::: "memory")
; template <class Epi, class Sched, bool ALIGN_EPI = false, bool SP2 = false>
; __device__ __forceinline__ void gemm_phase(PG8_LAS unsigned char* lds, const Gemm g, const Sched& S, const Epi& E) {
;     ...
;         for (int t = 0; t < nt; t += 2) {
;             const bool last = (t == nt - 2);
;             const char* a1 = cA + (size_t)(t + 1) * kstep;
;             const char* a2 = last ? nA : cA + (size_t)(t + 2) * kstep; const char* b2 = last ? nB : cB + (size_t)(t + 2) * kstep;
;             const char* a3 = a2 + kstep; const char* b3 = b2 + kstep;
;             if (last && has_next) S.a_ready(nxt);
;     ...
;             PG8_LDB(B0, 1, 0); PG8_LDB(B1, 1, 1); PG8_SCHED; PG8_LDA(At, 1, 0); PG8_STAGE(PG8_SA(0, 1), a2 + hstep, voffA);
;             PG8_WAIT_V(8); PG8_WAIT_L(0); PG8_BAR; PG8_MMA(0, 0, At, B0); PG8_MMA(0, 1, At, B1); PG8_BAR; PG8_SCHED;
;             PG8_LDA(At, 1, 1); PG8_STAGE(PG8_SB(1, 0), b3, voffB); PG8_STAGE(PG8_SB(1, 1), b3 + hstep, voffB); PG8_STAGE(PG8_SA(1, 0), a3, voffA);
;             PG8_WAIT_V(8); PG8_WAIT_L(0); PG8_BAR; PG8_MMA(1, 0, At, B0); PG8_MMA(1, 1, At, B1); PG8_BAR; PG8_SCHED;
	s_add_i32 s84, 0, 0x18000
	v_add_u32_e32 v140, s84, v159
	s_add_i32 s85, 0, 0x1c000
	ds_read_b128 v[150:153], v140
	ds_read_b128 v[154:157], v140 offset:1024
	ds_read_b128 v[166:169], v140 offset:2048
	ds_read_b128 v[170:173], v140 offset:3072
	v_add_u32_e32 v140, s85, v159
	ds_read_b128 v[174:177], v140
	ds_read_b128 v[178:181], v140 offset:1024
	ds_read_b128 v[182:185], v140 offset:2048
	ds_read_b128 v[186:189], v140 offset:3072
	s_add_u32 s34, s34, 0x80000
	s_addc_u32 s35, s35, 0
	s_mov_b32 m0, s41
	ds_read_b128 v[190:193], v163 offset:32768
	ds_read_b128 v[194:197], v163 offset:33792
	ds_read_b128 v[198:201], v163 offset:34816
	ds_read_b128 v[206:209], v163 offset:35840
	ds_read_b128 v[210:213], v163 offset:36864
	ds_read_b128 v[214:217], v163 offset:37888
	ds_read_b128 v[218:221], v163 offset:38912
	ds_read_b128 v[222:225], v163 offset:39936
	global_load_lds_dwordx4 v132, s[34:35]
	s_mov_b32 m0, s42
	s_nop 0
	global_load_lds_dwordx4 v136, s[34:35]
	s_waitcnt vmcnt(8)
	s_waitcnt lgkmcnt(0)
	s_barrier
	s_setprio 1
	s_waitcnt lgkmcnt(0)
	v_mfma_f32_16x16x32_bf16 v[126:129], v[150:153], v[190:193], v[126:129]
	v_mfma_f32_16x16x32_bf16 v[122:125], v[166:169], v[190:193], v[122:125]
	v_mfma_f32_16x16x32_bf16 v[110:113], v[150:153], v[198:201], v[110:113]
	v_mfma_f32_16x16x32_bf16 v[106:109], v[166:169], v[198:201], v[106:109]
	v_mfma_f32_16x16x32_bf16 v[94:97], v[150:153], v[210:213], v[94:97]
	v_mfma_f32_16x16x32_bf16 v[90:93], v[166:169], v[210:213], v[90:93]
	v_mfma_f32_16x16x32_bf16 v[78:81], v[150:153], v[218:221], v[78:81]
	v_mfma_f32_16x16x32_bf16 v[74:77], v[166:169], v[218:221], v[74:77]
	v_mfma_f32_16x16x32_bf16 v[126:129], v[154:157], v[194:197], v[126:129]
	v_mfma_f32_16x16x32_bf16 v[122:125], v[170:173], v[194:197], v[122:125]
	v_mfma_f32_16x16x32_bf16 v[110:113], v[154:157], v[206:209], v[110:113]
	v_mfma_f32_16x16x32_bf16 v[106:109], v[170:173], v[206:209], v[106:109]
	v_mfma_f32_16x16x32_bf16 v[94:97], v[154:157], v[214:217], v[94:97]
	v_mfma_f32_16x16x32_bf16 v[90:93], v[170:173], v[214:217], v[90:93]
	v_mfma_f32_16x16x32_bf16 v[78:81], v[154:157], v[222:225], v[78:81]
	v_mfma_f32_16x16x32_bf16 v[74:77], v[170:173], v[222:225], v[74:77]
	s_setprio 0
	s_setprio 1
	v_mfma_f32_16x16x32_bf16 v[118:121], v[174:177], v[190:193], v[118:121]
	v_mfma_f32_16x16x32_bf16 v[114:117], v[182:185], v[190:193], v[114:117]
	v_mfma_f32_16x16x32_bf16 v[102:105], v[174:177], v[198:201], v[102:105]
	v_mfma_f32_16x16x32_bf16 v[98:101], v[182:185], v[198:201], v[98:101]
	v_mfma_f32_16x16x32_bf16 v[86:89], v[174:177], v[210:213], v[86:89]
	v_mfma_f32_16x16x32_bf16 v[82:85], v[182:185], v[210:213], v[82:85]
	v_mfma_f32_16x16x32_bf16 v[70:73], v[174:177], v[218:221], v[70:73]
	v_mfma_f32_16x16x32_bf16 v[66:69], v[182:185], v[218:221], v[66:69]
	v_mfma_f32_16x16x32_bf16 v[118:121], v[178:181], v[194:197], v[118:121]
	v_mfma_f32_16x16x32_bf16 v[114:117], v[186:189], v[194:197], v[114:117]
	v_mfma_f32_16x16x32_bf16 v[102:105], v[178:181], v[206:209], v[102:105]
	v_mfma_f32_16x16x32_bf16 v[98:101], v[186:189], v[206:209], v[98:101]
	v_mfma_f32_16x16x32_bf16 v[86:89], v[178:181], v[214:217], v[86:89]
	v_mfma_f32_16x16x32_bf16 v[82:85], v[186:189], v[214:217], v[82:85]
	v_mfma_f32_16x16x32_bf16 v[70:73], v[178:181], v[222:225], v[70:73]
	v_mfma_f32_16x16x32_bf16 v[66:69], v[186:189], v[222:225], v[66:69]
	s_setprio 0
	s_barrier
	s_add_i32 s34, s84, s36
	s_mov_b32 m0, s34
	ds_read_b128 v[190:193], v163 offset:49152
	ds_read_b128 v[194:197], v163 offset:50176
	ds_read_b128 v[198:201], v163 offset:51200
	ds_read_b128 v[206:209], v163 offset:52224
	ds_read_b128 v[210:213], v163 offset:53248
	ds_read_b128 v[214:217], v163 offset:54272
	ds_read_b128 v[218:221], v163 offset:55296
	ds_read_b128 v[222:225], v163 offset:56320
	global_load_lds_dwordx4 v134, s[64:65]
	s_add_i32 m0, s34, 0x2000
	s_add_u32 s30, s30, 0x80080
	s_addc_u32 s31, s31, 0
	s_add_i32 s34, s85, s36
	global_load_lds_dwordx4 v138, s[64:65]
	s_mov_b32 m0, s34
	s_nop 0
	global_load_lds_dwordx4 v134, s[30:31]
	s_add_i32 m0, s34, 0x2000
	s_nop 0
	global_load_lds_dwordx4 v138, s[30:31]
	s_mov_b32 m0, s77
	s_nop 0
	global_load_lds_dwordx4 v132, s[66:67]
	s_mov_b32 m0, s78
	s_nop 0
	global_load_lds_dwordx4 v136, s[66:67]
	s_waitcnt vmcnt(8)
	s_waitcnt lgkmcnt(0)
	s_barrier
	s_setprio 1
	s_waitcnt lgkmcnt(0)
	v_mfma_f32_16x16x32_bf16 v[62:65], v[150:153], v[190:193], v[62:65]
	v_mfma_f32_16x16x32_bf16 v[58:61], v[166:169], v[190:193], v[58:61]
	v_mfma_f32_16x16x32_bf16 v[46:49], v[150:153], v[198:201], v[46:49]
	v_mfma_f32_16x16x32_bf16 v[42:45], v[166:169], v[198:201], v[42:45]
	v_mfma_f32_16x16x32_bf16 v[30:33], v[150:153], v[210:213], v[30:33]
	v_mfma_f32_16x16x32_bf16 v[26:29], v[166:169], v[210:213], v[26:29]
	v_mfma_f32_16x16x32_bf16 v[14:17], v[150:153], v[218:221], v[14:17]
	v_mfma_f32_16x16x32_bf16 v[10:13], v[166:169], v[218:221], v[10:13]
	v_mfma_f32_16x16x32_bf16 v[62:65], v[154:157], v[194:197], v[62:65]
	v_mfma_f32_16x16x32_bf16 v[58:61], v[170:173], v[194:197], v[58:61]
	v_mfma_f32_16x16x32_bf16 v[46:49], v[154:157], v[206:209], v[46:49]
	v_mfma_f32_16x16x32_bf16 v[42:45], v[170:173], v[206:209], v[42:45]
	v_mfma_f32_16x16x32_bf16 v[30:33], v[154:157], v[214:217], v[30:33]
	v_mfma_f32_16x16x32_bf16 v[26:29], v[170:173], v[214:217], v[26:29]
	v_mfma_f32_16x16x32_bf16 v[14:17], v[154:157], v[222:225], v[14:17]
	v_mfma_f32_16x16x32_bf16 v[10:13], v[170:173], v[222:225], v[10:13]
	s_setprio 0
	s_setprio 1
	v_mfma_f32_16x16x32_bf16 v[54:57], v[174:177], v[190:193], v[54:57]
	v_mfma_f32_16x16x32_bf16 v[50:53], v[182:185], v[190:193], v[50:53]
	v_mfma_f32_16x16x32_bf16 v[38:41], v[174:177], v[198:201], v[38:41]
	v_mfma_f32_16x16x32_bf16 v[34:37], v[182:185], v[198:201], v[34:37]
	v_mfma_f32_16x16x32_bf16 v[22:25], v[174:177], v[210:213], v[22:25]
	v_mfma_f32_16x16x32_bf16 v[18:21], v[182:185], v[210:213], v[18:21]
	v_mfma_f32_16x16x32_bf16 v[6:9], v[174:177], v[218:221], v[6:9]
	v_mfma_f32_16x16x32_bf16 v[2:5], v[182:185], v[218:221], v[2:5]
	v_mfma_f32_16x16x32_bf16 v[54:57], v[178:181], v[194:197], v[54:57]
	v_mfma_f32_16x16x32_bf16 v[50:53], v[186:189], v[194:197], v[50:53]
	v_mfma_f32_16x16x32_bf16 v[38:41], v[178:181], v[206:209], v[38:41]
	v_mfma_f32_16x16x32_bf16 v[34:37], v[186:189], v[206:209], v[34:37]
	v_mfma_f32_16x16x32_bf16 v[22:25], v[178:181], v[214:217], v[22:25]
	v_mfma_f32_16x16x32_bf16 v[18:21], v[186:189], v[214:217], v[18:21]
	v_mfma_f32_16x16x32_bf16 v[6:9], v[178:181], v[222:225], v[6:9]
	v_mfma_f32_16x16x32_bf16 v[2:5], v[186:189], v[222:225], v[2:5]
	s_setprio 0
	s_barrier
	s_add_i32 s83, s83, 2
	s_add_u32 s28, s28, 0x100
	s_addc_u32 s29, s29, 0
	s_add_u32 s71, s71, 0x100
	s_addc_u32 s82, s82, 0
	s_cmp_gt_u32 s83, 29
	s_cbranch_scc0 .LBB0_203
	s_and_b64 vcc, exec, s[18:19]
	s_cbranch_vccz .LBB0_206
	s_barrier

; #define PG8_STAGE(bufoff, gbase, voff) do { _Pragma("unroll") for (int _i = 0; _i < 2; ++_i) \
;         __builtin_amdgcn_global_load_lds((const unsigned*)((const char*)(gbase) + (voff)[_i]), (PG8_LAS unsigned*)(lds + (bufoff) + ldsw + _i * 8192), 16, 0, 0); } while (0)
; #define PG8_LDA(dst, b, h) do { _Pragma("unroll") for (int m = 0; m < 4; ++m) _Pragma("unroll") for (int k = 0; k < 2; ++k) dst[m][k] = *(const PG8_LAS bf16x8*)(lds + PG8_SA(b, h) + aoff + m * 2048 + k * 1024); } while (0)
; #define PG8_LDB(dst, b, h) do { _Pragma("unroll") for (int n = 0; n < 2; ++n) _Pragma("unroll") for (int k = 0; k < 2; ++k) dst[n][k] = *(const PG8_LAS bf16x8*)(lds + PG8_SB(b, h) + boff + n * 2048 + k * 1024); } while (0)
; #define PG8_WAIT_V(n) asm volatile("s_waitcnt vmcnt(" #n ")" ::: "memory")
; template <class Epi, class Sched, bool ALIGN_EPI = false, bool SP2 = false>
; __device__ __forceinline__ void gemm_phase(PG8_LAS unsigned char* lds, const Gemm g, const Sched& S, const Epi& E) {
;     ...
;             const char* a1 = cA + (size_t)(t + 1) * kstep;
;             const char* a2 = last ? nA : cA + (size_t)(t + 2) * kstep; const char* b2 = last ? nB : cB + (size_t)(t + 2) * kstep;
;             const char* a3 = a2 + kstep; const char* b3 = b2 + kstep;
;             if (last && has_next) S.a_ready(nxt);
;             if constexpr (SP2) {
;             PG8_LDB(B0, 0, 0); PG8_LDB(B1, 0, 1); PG8_SCHED; PG8_LDA(At, 0, 0); PG8_STAGE(PG8_SA(1, 1), a1 + hstep, voffA);
;             PG8_WAIT_V(8); PG8_WAIT_L(0); PG8_BAR; PG8_MMA(0, 0, At, B0); PG8_MMA(0, 1, At, B1); PG8_BAR; PG8_SCHED;
;             PG8_LDA(At, 0, 1); PG8_STAGE(PG8_SB(0, 0), b2, voffB); PG8_STAGE(PG8_SB(0, 1), b2 + hstep, voffB); PG8_STAGE(PG8_SA(0, 0), a2, voffA);
;             PG8_WAIT_V(8); PG8_WAIT_L(0); PG8_BAR; PG8_MMA(1, 0, At, B0); PG8_MMA(1, 1, At, B1); PG8_BAR; PG8_SCHED;
;             PG8_LDB(B0, 1, 0); PG8_LDB(B1, 1, 1); PG8_SCHED; PG8_LDA(At, 1, 0); PG8_STAGE(PG8_SA(0, 1), a2 + hstep, voffA);
;             PG8_WAIT_V(8); PG8_WAIT_L(0); PG8_BAR; PG8_MMA(0, 0, At, B0); PG8_MMA(0, 1, At, B1); PG8_BAR; PG8_SCHED;
;             PG8_LDA(At, 1, 1); PG8_STAGE(PG8_SB(1, 0), b3, voffB); PG8_STAGE(PG8_SB(1, 1), b3 + hstep, voffB); PG8_STAGE(PG8_SA(1, 0), a3, voffA);
;             PG8_WAIT_V(8); PG8_WAIT_L(0); PG8_BAR; PG8_MMA(1, 0, At, B0); PG8_MMA(1, 1, At, B1); PG8_BAR; PG8_SCHED;
.LBB0_615:
	ds_read_b128 v[148:151], v155
	ds_read_b128 v[164:167], v155 offset:1024
	ds_read_b128 v[168:171], v155 offset:2048
	ds_read_b128 v[172:175], v155 offset:3072
	ds_read_b128 v[176:179], v156
	ds_read_b128 v[180:183], v156 offset:1024
	ds_read_b128 v[184:187], v156 offset:2048
	ds_read_b128 v[188:191], v156 offset:3072
	s_add_u32 s24, s22, 0xfff80080
	s_addc_u32 s25, s23, -1
	s_cmp_eq_u32 s79, 28
	s_cselect_b32 s27, s17, s25
	s_cselect_b32 s26, s75, s24
	s_cselect_b32 s25, s15, s78
	s_cselect_b32 s24, s76, s77
	s_add_i32 m0, s37, 0xc000
	ds_read_b128 v[192:195], v157
	ds_read_b128 v[196:199], v157 offset:1024
	ds_read_b128 v[206:209], v157 offset:2048
	ds_read_b128 v[210:213], v157 offset:3072
	ds_read_b128 v[214:217], v157 offset:4096
	ds_read_b128 v[218:221], v157 offset:5120
	ds_read_b128 v[222:225], v157 offset:6144
	ds_read_b128 v[226:229], v157 offset:7168
	global_load_lds_dwordx4 v138, s[22:23]
	s_add_i32 m0, s37, 0xe000
	s_nop 0
	global_load_lds_dwordx4 v140, s[22:23]
	s_waitcnt vmcnt(8)
	s_waitcnt lgkmcnt(0)
	s_barrier
	s_setprio 1
	s_waitcnt lgkmcnt(0)
	v_mfma_f32_16x16x32_bf16 v[126:129], v[148:151], v[192:195], v[126:129]
	v_mfma_f32_16x16x32_bf16 v[122:125], v[168:171], v[192:195], v[122:125]
	v_mfma_f32_16x16x32_bf16 v[110:113], v[148:151], v[206:209], v[110:113]
	v_mfma_f32_16x16x32_bf16 v[106:109], v[168:171], v[206:209], v[106:109]
	v_mfma_f32_16x16x32_bf16 v[94:97], v[148:151], v[214:217], v[94:97]
	v_mfma_f32_16x16x32_bf16 v[90:93], v[168:171], v[214:217], v[90:93]
	v_mfma_f32_16x16x32_bf16 v[78:81], v[148:151], v[222:225], v[78:81]
	v_mfma_f32_16x16x32_bf16 v[74:77], v[168:171], v[222:225], v[74:77]
	v_mfma_f32_16x16x32_bf16 v[126:129], v[164:167], v[196:199], v[126:129]
	v_mfma_f32_16x16x32_bf16 v[122:125], v[172:175], v[196:199], v[122:125]
	v_mfma_f32_16x16x32_bf16 v[110:113], v[164:167], v[210:213], v[110:113]
	v_mfma_f32_16x16x32_bf16 v[106:109], v[172:175], v[210:213], v[106:109]
	v_mfma_f32_16x16x32_bf16 v[94:97], v[164:167], v[218:221], v[94:97]
	v_mfma_f32_16x16x32_bf16 v[90:93], v[172:175], v[218:221], v[90:93]
	v_mfma_f32_16x16x32_bf16 v[78:81], v[164:167], v[226:229], v[78:81]
	v_mfma_f32_16x16x32_bf16 v[74:77], v[172:175], v[226:229], v[74:77]
	s_setprio 0
	s_setprio 1
	v_mfma_f32_16x16x32_bf16 v[118:121], v[176:179], v[192:195], v[118:121]
	v_mfma_f32_16x16x32_bf16 v[114:117], v[184:187], v[192:195], v[114:117]
	v_mfma_f32_16x16x32_bf16 v[102:105], v[176:179], v[206:209], v[102:105]
	v_mfma_f32_16x16x32_bf16 v[98:101], v[184:187], v[206:209], v[98:101]
	v_mfma_f32_16x16x32_bf16 v[86:89], v[176:179], v[214:217], v[86:89]
	v_mfma_f32_16x16x32_bf16 v[82:85], v[184:187], v[214:217], v[82:85]
	v_mfma_f32_16x16x32_bf16 v[70:73], v[176:179], v[222:225], v[70:73]
	v_mfma_f32_16x16x32_bf16 v[66:69], v[184:187], v[222:225], v[66:69]
	v_mfma_f32_16x16x32_bf16 v[118:121], v[180:183], v[196:199], v[118:121]
	v_mfma_f32_16x16x32_bf16 v[114:117], v[188:191], v[196:199], v[114:117]
	v_mfma_f32_16x16x32_bf16 v[102:105], v[180:183], v[210:213], v[102:105]
	v_mfma_f32_16x16x32_bf16 v[98:101], v[188:191], v[210:213], v[98:101]
	v_mfma_f32_16x16x32_bf16 v[86:89], v[180:183], v[218:221], v[86:89]
	v_mfma_f32_16x16x32_bf16 v[82:85], v[188:191], v[218:221], v[82:85]
	v_mfma_f32_16x16x32_bf16 v[70:73], v[180:183], v[226:229], v[70:73]
	v_mfma_f32_16x16x32_bf16 v[66:69], v[188:191], v[226:229], v[66:69]
	s_setprio 0
	s_barrier
	s_add_i32 s64, s45, s36
	s_add_u32 s66, s24, 0x80
	s_addc_u32 s67, s25, 0
	s_mov_b32 m0, s64
	ds_read_b128 v[192:195], v157 offset:16384
	ds_read_b128 v[196:199], v157 offset:17408
	ds_read_b128 v[206:209], v157 offset:18432
	ds_read_b128 v[210:213], v157 offset:19456
	ds_read_b128 v[214:217], v157 offset:20480
	ds_read_b128 v[218:221], v157 offset:21504
	ds_read_b128 v[222:225], v157 offset:22528
	ds_read_b128 v[226:229], v157 offset:23552
	global_load_lds_dwordx4 v132, s[24:25]
	s_add_i32 m0, s64, 0x2000
	s_add_u32 s80, s24, 0x80000
	s_addc_u32 s81, s25, 0
	s_add_i32 s64, s70, s36
	global_load_lds_dwordx4 v136, s[24:25]
	s_mov_b32 m0, s64
	s_add_u32 s68, s26, 0x80
	s_addc_u32 s69, s27, 0
	global_load_lds_dwordx4 v132, s[80:81]
	s_add_i32 m0, s64, 0x2000
	s_nop 0
	global_load_lds_dwordx4 v136, s[80:81]
	s_mov_b32 m0, s37
	s_nop 0
	global_load_lds_dwordx4 v130, s[26:27]
	s_mov_b32 m0, s38
	s_nop 0
	global_load_lds_dwordx4 v134, s[26:27]
	s_waitcnt vmcnt(8)
	s_waitcnt lgkmcnt(0)
	s_barrier
	s_setprio 1
	s_waitcnt lgkmcnt(0)
	v_mfma_f32_16x16x32_bf16 v[62:65], v[148:151], v[192:195], v[62:65]
	v_mfma_f32_16x16x32_bf16 v[58:61], v[168:171], v[192:195], v[58:61]
	v_mfma_f32_16x16x32_bf16 v[46:49], v[148:151], v[206:209], v[46:49]
	v_mfma_f32_16x16x32_bf16 v[42:45], v[168:171], v[206:209], v[42:45]
	v_mfma_f32_16x16x32_bf16 v[30:33], v[148:151], v[214:217], v[30:33]
	v_mfma_f32_16x16x32_bf16 v[26:29], v[168:171], v[214:217], v[26:29]
	v_mfma_f32_16x16x32_bf16 v[14:17], v[148:151], v[222:225], v[14:17]
	v_mfma_f32_16x16x32_bf16 v[10:13], v[168:171], v[222:225], v[10:13]
	v_mfma_f32_16x16x32_bf16 v[62:65], v[164:167], v[196:199], v[62:65]
	v_mfma_f32_16x16x32_bf16 v[58:61], v[172:175], v[196:199], v[58:61]
	v_mfma_f32_16x16x32_bf16 v[46:49], v[164:167], v[210:213], v[46:49]
	v_mfma_f32_16x16x32_bf16 v[42:45], v[172:175], v[210:213], v[42:45]
	v_mfma_f32_16x16x32_bf16 v[30:33], v[164:167], v[218:221], v[30:33]
	v_mfma_f32_16x16x32_bf16 v[26:29], v[172:175], v[218:221], v[26:29]
	v_mfma_f32_16x16x32_bf16 v[14:17], v[164:167], v[226:229], v[14:17]
	v_mfma_f32_16x16x32_bf16 v[10:13], v[172:175], v[226:229], v[10:13]
	s_setprio 0
	s_setprio 1
	v_mfma_f32_16x16x32_bf16 v[54:57], v[176:179], v[192:195], v[54:57]
	v_mfma_f32_16x16x32_bf16 v[50:53], v[184:187], v[192:195], v[50:53]
	v_mfma_f32_16x16x32_bf16 v[38:41], v[176:179], v[206:209], v[38:41]
	v_mfma_f32_16x16x32_bf16 v[34:37], v[184:187], v[206:209], v[34:37]
	v_mfma_f32_16x16x32_bf16 v[22:25], v[176:179], v[214:217], v[22:25]
	v_mfma_f32_16x16x32_bf16 v[18:21], v[184:187], v[214:217], v[18:21]
	v_mfma_f32_16x16x32_bf16 v[6:9], v[176:179], v[222:225], v[6:9]
	v_mfma_f32_16x16x32_bf16 v[2:5], v[184:187], v[222:225], v[2:5]
	v_mfma_f32_16x16x32_bf16 v[54:57], v[180:183], v[196:199], v[54:57]
	v_mfma_f32_16x16x32_bf16 v[50:53], v[188:191], v[196:199], v[50:53]
	v_mfma_f32_16x16x32_bf16 v[38:41], v[180:183], v[210:213], v[38:41]
	v_mfma_f32_16x16x32_bf16 v[34:37], v[188:191], v[210:213], v[34:37]
	v_mfma_f32_16x16x32_bf16 v[22:25], v[180:183], v[218:221], v[22:25]
	v_mfma_f32_16x16x32_bf16 v[18:21], v[188:191], v[218:221], v[18:21]
	v_mfma_f32_16x16x32_bf16 v[6:9], v[180:183], v[226:229], v[6:9]
	v_mfma_f32_16x16x32_bf16 v[2:5], v[188:191], v[226:229], v[2:5]
	s_setprio 0
	s_barrier
; #define PG8_STAGE(bufoff, gbase, voff) do { _Pragma("unroll") for (int _i = 0; _i < 2; ++_i) \
;         __builtin_amdgcn_global_load_lds((const unsigned*)((const char*)(gbase) + (voff)[_i]), (PG8_LAS unsigned*)(lds + (bufoff) + ldsw + _i * 8192), 16, 0, 0); } while (0)
; #define PG8_LDA(dst, b, h) do { _Pragma("unroll") for (int m = 0; m < 4; ++m) _Pragma("unroll") for (int k = 0; k < 2; ++k) dst[m][k] = *(const PG8_LAS bf16x8*)(lds + PG8_SA(b, h) + aoff + m * 2048 + k * 1024); } while (0)
; #define PG8_LDB(dst, b, h) do { _Pragma("unroll") for (int n = 0; n < 2; ++n) _Pragma("unroll") for (int k = 0; k < 2; ++k) dst[n][k] = *(const PG8_LAS bf16x8*)(lds + PG8_SB(b, h) + boff + n * 2048 + k * 1024); } while (0)
; #define PG8_MMA(ai, bj, At, Bt) do { __builtin_amdgcn_s_setprio(1); _Pragma("unroll") for (int m = 0; m < 4; ++m) _Pragma("unroll") for (int n = 0; n < 2; ++n) _Pragma("unroll") for (int k = 0; k < 2; ++k) \
;         acc[ai][bj][m][n] = __builtin_amdgcn_mfma_f32_16x16x32_bf16(Bt[n][k], At[m][k], acc[ai][bj][m][n], 0, 0, 0); __builtin_amdgcn_s_setprio(0); } while (0)
; #define PG8_WAIT_V(n) asm volatile("s_waitcnt vmcnt(" #n ")" ::: "memory")
; #define PG8_WAIT_L(n) asm volatile("s_waitcnt lgkmcnt(" #n ")" ::: "memory")
; template <class Epi, class Sched, bool ALIGN_EPI = false, bool SP2 = false>
; __device__ __forceinline__ void gemm_phase(PG8_LAS unsigned char* lds, const Gemm g, const Sched& S, const Epi& E) {
;     ...
;         for (int t = 0; t < nt; t += 2) {
;             const bool last = (t == nt - 2);
;             const char* a1 = cA + (size_t)(t + 1) * kstep;
;             const char* a2 = last ? nA : cA + (size_t)(t + 2) * kstep; const char* b2 = last ? nB : cB + (size_t)(t + 2) * kstep;
;             const char* a3 = a2 + kstep; const char* b3 = b2 + kstep;
;             if (last && has_next) S.a_ready(nxt);
;     ...
;             PG8_LDB(B0, 1, 0); PG8_LDB(B1, 1, 1); PG8_SCHED; PG8_LDA(At, 1, 0); PG8_STAGE(PG8_SA(0, 1), a2 + hstep, voffA);
;             PG8_WAIT_V(8); PG8_WAIT_L(0); PG8_BAR; PG8_MMA(0, 0, At, B0); PG8_MMA(0, 1, At, B1); PG8_BAR; PG8_SCHED;
;             PG8_LDA(At, 1, 1); PG8_STAGE(PG8_SB(1, 0), b3, voffB); PG8_STAGE(PG8_SB(1, 1), b3 + hstep, voffB); PG8_STAGE(PG8_SA(1, 0), a3, voffA);
;             PG8_WAIT_V(8); PG8_WAIT_L(0); PG8_BAR; PG8_MMA(1, 0, At, B0); PG8_MMA(1, 1, At, B1); PG8_BAR; PG8_SCHED;
	s_add_i32 s64, 0, 0x18000
	v_add_u32_e32 v159, s64, v153
	s_add_i32 s65, 0, 0x1c000
	ds_read_b128 v[148:151], v159
	ds_read_b128 v[164:167], v159 offset:1024
	ds_read_b128 v[168:171], v159 offset:2048
	ds_read_b128 v[172:175], v159 offset:3072
	v_add_u32_e32 v159, s65, v153
	ds_read_b128 v[176:179], v159
	ds_read_b128 v[180:183], v159 offset:1024
	ds_read_b128 v[184:187], v159 offset:2048
	ds_read_b128 v[188:191], v159 offset:3072
	s_add_u32 s26, s26, 0x80000
	s_addc_u32 s27, s27, 0
	s_mov_b32 m0, s39
	ds_read_b128 v[192:195], v157 offset:32768
	ds_read_b128 v[196:199], v157 offset:33792
	ds_read_b128 v[206:209], v157 offset:34816
	ds_read_b128 v[210:213], v157 offset:35840
	ds_read_b128 v[214:217], v157 offset:36864
	ds_read_b128 v[218:221], v157 offset:37888
	ds_read_b128 v[222:225], v157 offset:38912
	ds_read_b128 v[226:229], v157 offset:39936
	global_load_lds_dwordx4 v130, s[26:27]
	s_mov_b32 m0, s40
	s_nop 0
	global_load_lds_dwordx4 v134, s[26:27]
	s_waitcnt vmcnt(8)
	s_waitcnt lgkmcnt(0)
	s_barrier
	s_setprio 1
	s_waitcnt lgkmcnt(0)
	v_mfma_f32_16x16x32_bf16 v[126:129], v[148:151], v[192:195], v[126:129]
	v_mfma_f32_16x16x32_bf16 v[122:125], v[168:171], v[192:195], v[122:125]
	v_mfma_f32_16x16x32_bf16 v[110:113], v[148:151], v[206:209], v[110:113]
	v_mfma_f32_16x16x32_bf16 v[106:109], v[168:171], v[206:209], v[106:109]
	v_mfma_f32_16x16x32_bf16 v[94:97], v[148:151], v[214:217], v[94:97]
	v_mfma_f32_16x16x32_bf16 v[90:93], v[168:171], v[214:217], v[90:93]
	v_mfma_f32_16x16x32_bf16 v[78:81], v[148:151], v[222:225], v[78:81]
	v_mfma_f32_16x16x32_bf16 v[74:77], v[168:171], v[222:225], v[74:77]
	v_mfma_f32_16x16x32_bf16 v[126:129], v[164:167], v[196:199], v[126:129]
	v_mfma_f32_16x16x32_bf16 v[122:125], v[172:175], v[196:199], v[122:125]
	v_mfma_f32_16x16x32_bf16 v[110:113], v[164:167], v[210:213], v[110:113]
	v_mfma_f32_16x16x32_bf16 v[106:109], v[172:175], v[210:213], v[106:109]
	v_mfma_f32_16x16x32_bf16 v[94:97], v[164:167], v[218:221], v[94:97]
	v_mfma_f32_16x16x32_bf16 v[90:93], v[172:175], v[218:221], v[90:93]
	v_mfma_f32_16x16x32_bf16 v[78:81], v[164:167], v[226:229], v[78:81]
	v_mfma_f32_16x16x32_bf16 v[74:77], v[172:175], v[226:229], v[74:77]
	s_setprio 0
	s_setprio 1
	v_mfma_f32_16x16x32_bf16 v[118:121], v[176:179], v[192:195], v[118:121]
	v_mfma_f32_16x16x32_bf16 v[114:117], v[184:187], v[192:195], v[114:117]
	v_mfma_f32_16x16x32_bf16 v[102:105], v[176:179], v[206:209], v[102:105]
	v_mfma_f32_16x16x32_bf16 v[98:101], v[184:187], v[206:209], v[98:101]
	v_mfma_f32_16x16x32_bf16 v[86:89], v[176:179], v[214:217], v[86:89]
	v_mfma_f32_16x16x32_bf16 v[82:85], v[184:187], v[214:217], v[82:85]
	v_mfma_f32_16x16x32_bf16 v[70:73], v[176:179], v[222:225], v[70:73]
	v_mfma_f32_16x16x32_bf16 v[66:69], v[184:187], v[222:225], v[66:69]
	v_mfma_f32_16x16x32_bf16 v[118:121], v[180:183], v[196:199], v[118:121]
	v_mfma_f32_16x16x32_bf16 v[114:117], v[188:191], v[196:199], v[114:117]
	v_mfma_f32_16x16x32_bf16 v[102:105], v[180:183], v[210:213], v[102:105]
	v_mfma_f32_16x16x32_bf16 v[98:101], v[188:191], v[210:213], v[98:101]
	v_mfma_f32_16x16x32_bf16 v[86:89], v[180:183], v[218:221], v[86:89]
	v_mfma_f32_16x16x32_bf16 v[82:85], v[188:191], v[218:221], v[82:85]
	v_mfma_f32_16x16x32_bf16 v[70:73], v[180:183], v[226:229], v[70:73]
	v_mfma_f32_16x16x32_bf16 v[66:69], v[188:191], v[226:229], v[66:69]
	s_setprio 0
	s_barrier
	s_add_i32 s26, s64, s36
	s_mov_b32 m0, s26
	ds_read_b128 v[192:195], v157 offset:49152
	ds_read_b128 v[196:199], v157 offset:50176
	ds_read_b128 v[206:209], v157 offset:51200
	ds_read_b128 v[210:213], v157 offset:52224
	ds_read_b128 v[214:217], v157 offset:53248
	ds_read_b128 v[218:221], v157 offset:54272
	ds_read_b128 v[222:225], v157 offset:55296
	ds_read_b128 v[226:229], v157 offset:56320
	global_load_lds_dwordx4 v132, s[66:67]
	s_add_i32 m0, s26, 0x2000
	s_add_u32 s24, s24, 0x80080
	s_addc_u32 s25, s25, 0
	s_add_i32 s26, s65, s36
	global_load_lds_dwordx4 v136, s[66:67]
	s_mov_b32 m0, s26
	s_nop 0
	global_load_lds_dwordx4 v132, s[24:25]
	s_add_i32 m0, s26, 0x2000
	s_nop 0
	global_load_lds_dwordx4 v136, s[24:25]
	s_mov_b32 m0, s43
	s_nop 0
	global_load_lds_dwordx4 v130, s[68:69]
	s_mov_b32 m0, s44
	s_nop 0
	global_load_lds_dwordx4 v134, s[68:69]
	s_waitcnt vmcnt(8)
	s_waitcnt lgkmcnt(0)
	s_barrier
	s_setprio 1
	s_waitcnt lgkmcnt(0)
	v_mfma_f32_16x16x32_bf16 v[62:65], v[148:151], v[192:195], v[62:65]
	v_mfma_f32_16x16x32_bf16 v[58:61], v[168:171], v[192:195], v[58:61]
	v_mfma_f32_16x16x32_bf16 v[46:49], v[148:151], v[206:209], v[46:49]
	v_mfma_f32_16x16x32_bf16 v[42:45], v[168:171], v[206:209], v[42:45]
	v_mfma_f32_16x16x32_bf16 v[30:33], v[148:151], v[214:217], v[30:33]
	v_mfma_f32_16x16x32_bf16 v[26:29], v[168:171], v[214:217], v[26:29]
	v_mfma_f32_16x16x32_bf16 v[14:17], v[148:151], v[222:225], v[14:17]
	v_mfma_f32_16x16x32_bf16 v[10:13], v[168:171], v[222:225], v[10:13]
	v_mfma_f32_16x16x32_bf16 v[62:65], v[164:167], v[196:199], v[62:65]
	v_mfma_f32_16x16x32_bf16 v[58:61], v[172:175], v[196:199], v[58:61]
	v_mfma_f32_16x16x32_bf16 v[46:49], v[164:167], v[210:213], v[46:49]
	v_mfma_f32_16x16x32_bf16 v[42:45], v[172:175], v[210:213], v[42:45]
	v_mfma_f32_16x16x32_bf16 v[30:33], v[164:167], v[218:221], v[30:33]
	v_mfma_f32_16x16x32_bf16 v[26:29], v[172:175], v[218:221], v[26:29]
	v_mfma_f32_16x16x32_bf16 v[14:17], v[164:167], v[226:229], v[14:17]
	v_mfma_f32_16x16x32_bf16 v[10:13], v[172:175], v[226:229], v[10:13]
	s_setprio 0
	s_setprio 1
	v_mfma_f32_16x16x32_bf16 v[54:57], v[176:179], v[192:195], v[54:57]
	v_mfma_f32_16x16x32_bf16 v[50:53], v[184:187], v[192:195], v[50:53]
	v_mfma_f32_16x16x32_bf16 v[38:41], v[176:179], v[206:209], v[38:41]
	v_mfma_f32_16x16x32_bf16 v[34:37], v[184:187], v[206:209], v[34:37]
	v_mfma_f32_16x16x32_bf16 v[22:25], v[176:179], v[214:217], v[22:25]
	v_mfma_f32_16x16x32_bf16 v[18:21], v[184:187], v[214:217], v[18:21]
	v_mfma_f32_16x16x32_bf16 v[6:9], v[176:179], v[222:225], v[6:9]
	v_mfma_f32_16x16x32_bf16 v[2:5], v[184:187], v[222:225], v[2:5]
	v_mfma_f32_16x16x32_bf16 v[54:57], v[180:183], v[196:199], v[54:57]
	v_mfma_f32_16x16x32_bf16 v[50:53], v[188:191], v[196:199], v[50:53]
	v_mfma_f32_16x16x32_bf16 v[38:41], v[180:183], v[210:213], v[38:41]
	v_mfma_f32_16x16x32_bf16 v[34:37], v[188:191], v[210:213], v[34:37]
	v_mfma_f32_16x16x32_bf16 v[22:25], v[180:183], v[218:221], v[22:25]
	v_mfma_f32_16x16x32_bf16 v[18:21], v[188:191], v[218:221], v[18:21]
	v_mfma_f32_16x16x32_bf16 v[6:9], v[180:183], v[226:229], v[6:9]
	v_mfma_f32_16x16x32_bf16 v[2:5], v[188:191], v[226:229], v[2:5]
	s_setprio 0
	s_barrier
	s_add_i32 s79, s79, 2
	s_add_u32 s22, s22, 0x100
	s_addc_u32 s23, s23, 0
	s_add_u32 s77, s77, 0x100
	s_addc_u32 s78, s78, 0
	s_cmp_gt_u32 s79, 29
	s_cbranch_scc0 .LBB0_615
	s_and_b64 vcc, exec, s[12:13]
	s_cbranch_vccz .LBB0_618
	s_barrier

; #define PG8_STAGE(bufoff, gbase, voff) do { _Pragma("unroll") for (int _i = 0; _i < 2; ++_i) \
;         __builtin_amdgcn_global_load_lds((const unsigned*)((const char*)(gbase) + (voff)[_i]), (PG8_LAS unsigned*)(lds + (bufoff) + ldsw + _i * 8192), 16, 0, 0); } while (0)
; #define PG8_LDA(dst, b, h) do { _Pragma("unroll") for (int m = 0; m < 4; ++m) _Pragma("unroll") for (int k = 0; k < 2; ++k) dst[m][k] = *(const PG8_LAS bf16x8*)(lds + PG8_SA(b, h) + aoff + m * 2048 + k * 1024); } while (0)
; #define PG8_LDB(dst, b, h) do { _Pragma("unroll") for (int n = 0; n < 2; ++n) _Pragma("unroll") for (int k = 0; k < 2; ++k) dst[n][k] = *(const PG8_LAS bf16x8*)(lds + PG8_SB(b, h) + boff + n * 2048 + k * 1024); } while (0)
; #define PG8_WAIT_V(n) asm volatile("s_waitcnt vmcnt(" #n ")" ::: "memory")
; template <class Epi, class Sched, bool ALIGN_EPI = false, bool SP2 = false>
; __device__ __forceinline__ void gemm_phase(PG8_LAS unsigned char* lds, const Gemm g, const Sched& S, const Epi& E) {
;     ...
;             const char* a1 = cA + (size_t)(t + 1) * kstep;
;             const char* a2 = last ? nA : cA + (size_t)(t + 2) * kstep; const char* b2 = last ? nB : cB + (size_t)(t + 2) * kstep;
;             const char* a3 = a2 + kstep; const char* b3 = b2 + kstep;
;             if (last && has_next) S.a_ready(nxt);
;             if constexpr (SP2) {
;             PG8_LDB(B0, 0, 0); PG8_LDB(B1, 0, 1); PG8_SCHED; PG8_LDA(At, 0, 0); PG8_STAGE(PG8_SA(1, 1), a1 + hstep, voffA);
;             PG8_WAIT_V(8); PG8_WAIT_L(0); PG8_BAR; PG8_MMA(0, 0, At, B0); PG8_MMA(0, 1, At, B1); PG8_BAR; PG8_SCHED;
;             PG8_LDA(At, 0, 1); PG8_STAGE(PG8_SB(0, 0), b2, voffB); PG8_STAGE(PG8_SB(0, 1), b2 + hstep, voffB); PG8_STAGE(PG8_SA(0, 0), a2, voffA);
;             PG8_WAIT_V(8); PG8_WAIT_L(0); PG8_BAR; PG8_MMA(1, 0, At, B0); PG8_MMA(1, 1, At, B1); PG8_BAR; PG8_SCHED;
;             PG8_LDB(B0, 1, 0); PG8_LDB(B1, 1, 1); PG8_SCHED; PG8_LDA(At, 1, 0); PG8_STAGE(PG8_SA(0, 1), a2 + hstep, voffA);
;             PG8_WAIT_V(8); PG8_WAIT_L(0); PG8_BAR; PG8_MMA(0, 0, At, B0); PG8_MMA(0, 1, At, B1); PG8_BAR; PG8_SCHED;
;             PG8_LDA(At, 1, 1); PG8_STAGE(PG8_SB(1, 0), b3, voffB); PG8_STAGE(PG8_SB(1, 1), b3 + hstep, voffB); PG8_STAGE(PG8_SA(1, 0), a3, voffA);
;             PG8_WAIT_V(8); PG8_WAIT_L(0); PG8_BAR; PG8_MMA(1, 0, At, B0); PG8_MMA(1, 1, At, B1); PG8_BAR; PG8_SCHED;
.LBB0_765:
	ds_read_b128 v[152:155], v164
	ds_read_b128 v[156:159], v164 offset:1024
	ds_read_b128 v[170:173], v164 offset:2048
	ds_read_b128 v[174:177], v164 offset:3072
	ds_read_b128 v[178:181], v165
	ds_read_b128 v[182:185], v165 offset:1024
	ds_read_b128 v[186:189], v165 offset:2048
	ds_read_b128 v[190:193], v165 offset:3072
	s_add_u32 s30, s28, 0xfff80080
	s_addc_u32 s31, s29, -1
	s_cmp_eq_u32 s85, 28
	s_cselect_b32 s35, s6, s31
	s_cselect_b32 s34, s23, s30
	s_cselect_b32 s31, s21, s84
	s_cselect_b32 s30, s70, s71
	s_add_i32 m0, s41, 0xc000
	ds_read_b128 v[194:197], v166
	ds_read_b128 v[204:207], v166 offset:1024
	ds_read_b128 v[208:211], v166 offset:2048
	ds_read_b128 v[212:215], v166 offset:3072
	ds_read_b128 v[216:219], v166 offset:4096
	ds_read_b128 v[220:223], v166 offset:5120
	ds_read_b128 v[224:227], v166 offset:6144
	ds_read_b128 v[228:231], v166 offset:7168
	global_load_lds_dwordx4 v142, s[28:29]
	s_add_i32 m0, s41, 0xe000
	s_nop 0
	global_load_lds_dwordx4 v144, s[28:29]
	s_waitcnt vmcnt(8)
	s_waitcnt lgkmcnt(0)
	s_barrier
	s_setprio 1
	s_waitcnt lgkmcnt(0)
	v_mfma_f32_16x16x32_bf16 v[126:129], v[152:155], v[194:197], v[126:129]
	v_mfma_f32_16x16x32_bf16 v[122:125], v[170:173], v[194:197], v[122:125]
	v_mfma_f32_16x16x32_bf16 v[110:113], v[152:155], v[208:211], v[110:113]
	v_mfma_f32_16x16x32_bf16 v[106:109], v[170:173], v[208:211], v[106:109]
	v_mfma_f32_16x16x32_bf16 v[94:97], v[152:155], v[216:219], v[94:97]
	v_mfma_f32_16x16x32_bf16 v[90:93], v[170:173], v[216:219], v[90:93]
	v_mfma_f32_16x16x32_bf16 v[78:81], v[152:155], v[224:227], v[78:81]
	v_mfma_f32_16x16x32_bf16 v[74:77], v[170:173], v[224:227], v[74:77]
	v_mfma_f32_16x16x32_bf16 v[126:129], v[156:159], v[204:207], v[126:129]
	v_mfma_f32_16x16x32_bf16 v[122:125], v[174:177], v[204:207], v[122:125]
	v_mfma_f32_16x16x32_bf16 v[110:113], v[156:159], v[212:215], v[110:113]
	v_mfma_f32_16x16x32_bf16 v[106:109], v[174:177], v[212:215], v[106:109]
	v_mfma_f32_16x16x32_bf16 v[94:97], v[156:159], v[220:223], v[94:97]
	v_mfma_f32_16x16x32_bf16 v[90:93], v[174:177], v[220:223], v[90:93]
	v_mfma_f32_16x16x32_bf16 v[78:81], v[156:159], v[228:231], v[78:81]
	v_mfma_f32_16x16x32_bf16 v[74:77], v[174:177], v[228:231], v[74:77]
	s_setprio 0
	s_setprio 1
	v_mfma_f32_16x16x32_bf16 v[118:121], v[178:181], v[194:197], v[118:121]
	v_mfma_f32_16x16x32_bf16 v[114:117], v[186:189], v[194:197], v[114:117]
	v_mfma_f32_16x16x32_bf16 v[102:105], v[178:181], v[208:211], v[102:105]
	v_mfma_f32_16x16x32_bf16 v[98:101], v[186:189], v[208:211], v[98:101]
	v_mfma_f32_16x16x32_bf16 v[86:89], v[178:181], v[216:219], v[86:89]
	v_mfma_f32_16x16x32_bf16 v[82:85], v[186:189], v[216:219], v[82:85]
	v_mfma_f32_16x16x32_bf16 v[70:73], v[178:181], v[224:227], v[70:73]
	v_mfma_f32_16x16x32_bf16 v[66:69], v[186:189], v[224:227], v[66:69]
	v_mfma_f32_16x16x32_bf16 v[118:121], v[182:185], v[204:207], v[118:121]
	v_mfma_f32_16x16x32_bf16 v[114:117], v[190:193], v[204:207], v[114:117]
	v_mfma_f32_16x16x32_bf16 v[102:105], v[182:185], v[212:215], v[102:105]
	v_mfma_f32_16x16x32_bf16 v[98:101], v[190:193], v[212:215], v[98:101]
	v_mfma_f32_16x16x32_bf16 v[86:89], v[182:185], v[220:223], v[86:89]
	v_mfma_f32_16x16x32_bf16 v[82:85], v[190:193], v[220:223], v[82:85]
	v_mfma_f32_16x16x32_bf16 v[70:73], v[182:185], v[228:231], v[70:73]
	v_mfma_f32_16x16x32_bf16 v[66:69], v[190:193], v[228:231], v[66:69]
	s_setprio 0
	s_barrier
	s_add_i32 s64, s81, s36
	s_add_u32 s66, s30, 0x80
	s_addc_u32 s67, s31, 0
	s_mov_b32 m0, s64
	ds_read_b128 v[194:197], v166 offset:16384
	ds_read_b128 v[204:207], v166 offset:17408
	ds_read_b128 v[208:211], v166 offset:18432
	ds_read_b128 v[212:215], v166 offset:19456
	ds_read_b128 v[216:219], v166 offset:20480
	ds_read_b128 v[220:223], v166 offset:21504
	ds_read_b128 v[224:227], v166 offset:22528
	ds_read_b128 v[228:231], v166 offset:23552
	global_load_lds_dwordx4 v134, s[30:31]
	s_add_i32 m0, s64, 0x2000
	s_add_u32 s86, s30, 0x80000
	s_addc_u32 s87, s31, 0
	s_add_i32 s64, s82, s36
	global_load_lds_dwordx4 v138, s[30:31]
	s_mov_b32 m0, s64
	s_add_u32 s68, s34, 0x80
	s_addc_u32 s69, s35, 0
	global_load_lds_dwordx4 v134, s[86:87]
	s_add_i32 m0, s64, 0x2000
	s_nop 0
	global_load_lds_dwordx4 v138, s[86:87]
	s_mov_b32 m0, s41
	s_nop 0
	global_load_lds_dwordx4 v132, s[34:35]
	s_mov_b32 m0, s42
	s_nop 0
	global_load_lds_dwordx4 v136, s[34:35]
	s_waitcnt vmcnt(8)
	s_waitcnt lgkmcnt(0)
	s_barrier
	s_setprio 1
	s_waitcnt lgkmcnt(0)
	v_mfma_f32_16x16x32_bf16 v[62:65], v[152:155], v[194:197], v[62:65]
	v_mfma_f32_16x16x32_bf16 v[58:61], v[170:173], v[194:197], v[58:61]
	v_mfma_f32_16x16x32_bf16 v[46:49], v[152:155], v[208:211], v[46:49]
	v_mfma_f32_16x16x32_bf16 v[42:45], v[170:173], v[208:211], v[42:45]
	v_mfma_f32_16x16x32_bf16 v[30:33], v[152:155], v[216:219], v[30:33]
	v_mfma_f32_16x16x32_bf16 v[26:29], v[170:173], v[216:219], v[26:29]
	v_mfma_f32_16x16x32_bf16 v[14:17], v[152:155], v[224:227], v[14:17]
	v_mfma_f32_16x16x32_bf16 v[10:13], v[170:173], v[224:227], v[10:13]
	v_mfma_f32_16x16x32_bf16 v[62:65], v[156:159], v[204:207], v[62:65]
	v_mfma_f32_16x16x32_bf16 v[58:61], v[174:177], v[204:207], v[58:61]
	v_mfma_f32_16x16x32_bf16 v[46:49], v[156:159], v[212:215], v[46:49]
	v_mfma_f32_16x16x32_bf16 v[42:45], v[174:177], v[212:215], v[42:45]
	v_mfma_f32_16x16x32_bf16 v[30:33], v[156:159], v[220:223], v[30:33]
	v_mfma_f32_16x16x32_bf16 v[26:29], v[174:177], v[220:223], v[26:29]
	v_mfma_f32_16x16x32_bf16 v[14:17], v[156:159], v[228:231], v[14:17]
	v_mfma_f32_16x16x32_bf16 v[10:13], v[174:177], v[228:231], v[10:13]
	s_setprio 0
	s_setprio 1
	v_mfma_f32_16x16x32_bf16 v[54:57], v[178:181], v[194:197], v[54:57]
	v_mfma_f32_16x16x32_bf16 v[50:53], v[186:189], v[194:197], v[50:53]
	v_mfma_f32_16x16x32_bf16 v[38:41], v[178:181], v[208:211], v[38:41]
	v_mfma_f32_16x16x32_bf16 v[34:37], v[186:189], v[208:211], v[34:37]
	v_mfma_f32_16x16x32_bf16 v[22:25], v[178:181], v[216:219], v[22:25]
	v_mfma_f32_16x16x32_bf16 v[18:21], v[186:189], v[216:219], v[18:21]
	v_mfma_f32_16x16x32_bf16 v[6:9], v[178:181], v[224:227], v[6:9]
	v_mfma_f32_16x16x32_bf16 v[2:5], v[186:189], v[224:227], v[2:5]
	v_mfma_f32_16x16x32_bf16 v[54:57], v[182:185], v[204:207], v[54:57]
	v_mfma_f32_16x16x32_bf16 v[50:53], v[190:193], v[204:207], v[50:53]
	v_mfma_f32_16x16x32_bf16 v[38:41], v[182:185], v[212:215], v[38:41]
	v_mfma_f32_16x16x32_bf16 v[34:37], v[190:193], v[212:215], v[34:37]
	v_mfma_f32_16x16x32_bf16 v[22:25], v[182:185], v[220:223], v[22:25]
	v_mfma_f32_16x16x32_bf16 v[18:21], v[190:193], v[220:223], v[18:21]
	v_mfma_f32_16x16x32_bf16 v[6:9], v[182:185], v[228:231], v[6:9]
	v_mfma_f32_16x16x32_bf16 v[2:5], v[190:193], v[228:231], v[2:5]
	s_setprio 0
	s_barrier
; #define PG8_STAGE(bufoff, gbase, voff) do { _Pragma("unroll") for (int _i = 0; _i < 2; ++_i) \
;         __builtin_amdgcn_global_load_lds((const unsigned*)((const char*)(gbase) + (voff)[_i]), (PG8_LAS unsigned*)(lds + (bufoff) + ldsw + _i * 8192), 16, 0, 0); } while (0)
; #define PG8_LDA(dst, b, h) do { _Pragma("unroll") for (int m = 0; m < 4; ++m) _Pragma("unroll") for (int k = 0; k < 2; ++k) dst[m][k] = *(const PG8_LAS bf16x8*)(lds + PG8_SA(b, h) + aoff + m * 2048 + k * 1024); } while (0)
; #define PG8_LDB(dst, b, h) do { _Pragma("unroll") for (int n = 0; n < 2; ++n) _Pragma("unroll") for (int k = 0; k < 2; ++k) dst[n][k] = *(const PG8_LAS bf16x8*)(lds + PG8_SB(b, h) + boff + n * 2048 + k * 1024); } while (0)
; #define PG8_MMA(ai, bj, At, Bt) do { __builtin_amdgcn_s_setprio(1); _Pragma("unroll") for (int m = 0; m < 4; ++m) _Pragma("unroll") for (int n = 0; n < 2; ++n) _Pragma("unroll") for (int k = 0; k < 2; ++k) \
;         acc[ai][bj][m][n] = __builtin_amdgcn_mfma_f32_16x16x32_bf16(Bt[n][k], At[m][k], acc[ai][bj][m][n], 0, 0, 0); __builtin_amdgcn_s_setprio(0); } while (0)
; #define PG8_WAIT_V(n) asm volatile("s_waitcnt vmcnt(" #n ")" ::: "memory")
; #define PG8_WAIT_L(n) asm volatile("s_waitcnt lgkmcnt(" #n ")" ::: "memory")
; template <class Epi, class Sched, bool ALIGN_EPI = false, bool SP2 = false>
; __device__ __forceinline__ void gemm_phase(PG8_LAS unsigned char* lds, const Gemm g, const Sched& S, const Epi& E) {
;     ...
;         for (int t = 0; t < nt; t += 2) {
;             const bool last = (t == nt - 2);
;             const char* a1 = cA + (size_t)(t + 1) * kstep;
;             const char* a2 = last ? nA : cA + (size_t)(t + 2) * kstep; const char* b2 = last ? nB : cB + (size_t)(t + 2) * kstep;
;             const char* a3 = a2 + kstep; const char* b3 = b2 + kstep;
;             if (last && has_next) S.a_ready(nxt);
;     ...
;             PG8_LDB(B0, 1, 0); PG8_LDB(B1, 1, 1); PG8_SCHED; PG8_LDA(At, 1, 0); PG8_STAGE(PG8_SA(0, 1), a2 + hstep, voffA);
;             PG8_WAIT_V(8); PG8_WAIT_L(0); PG8_BAR; PG8_MMA(0, 0, At, B0); PG8_MMA(0, 1, At, B1); PG8_BAR; PG8_SCHED;
;             PG8_LDA(At, 1, 1); PG8_STAGE(PG8_SB(1, 0), b3, voffB); PG8_STAGE(PG8_SB(1, 1), b3 + hstep, voffB); PG8_STAGE(PG8_SA(1, 0), a3, voffA);
;             PG8_WAIT_V(8); PG8_WAIT_L(0); PG8_BAR; PG8_MMA(1, 0, At, B0); PG8_MMA(1, 1, At, B1); PG8_BAR; PG8_SCHED;
	s_add_i32 s64, 0, 0x18000
	v_add_u32_e32 v140, s64, v160
	s_add_i32 s65, 0, 0x1c000
	ds_read_b128 v[152:155], v140
	ds_read_b128 v[156:159], v140 offset:1024
	ds_read_b128 v[170:173], v140 offset:2048
	ds_read_b128 v[174:177], v140 offset:3072
	v_add_u32_e32 v140, s65, v160
	ds_read_b128 v[178:181], v140
	ds_read_b128 v[182:185], v140 offset:1024
	ds_read_b128 v[186:189], v140 offset:2048
	ds_read_b128 v[190:193], v140 offset:3072
	s_add_u32 s34, s34, 0x80000
	s_addc_u32 s35, s35, 0
	s_mov_b32 m0, s43
	ds_read_b128 v[194:197], v166 offset:32768
	ds_read_b128 v[204:207], v166 offset:33792
	ds_read_b128 v[208:211], v166 offset:34816
	ds_read_b128 v[212:215], v166 offset:35840
	ds_read_b128 v[216:219], v166 offset:36864
	ds_read_b128 v[220:223], v166 offset:37888
	ds_read_b128 v[224:227], v166 offset:38912
	ds_read_b128 v[228:231], v166 offset:39936
	global_load_lds_dwordx4 v132, s[34:35]
	s_mov_b32 m0, s44
	s_nop 0
	global_load_lds_dwordx4 v136, s[34:35]
	s_waitcnt vmcnt(8)
	s_waitcnt lgkmcnt(0)
	s_barrier
	s_setprio 1
	s_waitcnt lgkmcnt(0)
	v_mfma_f32_16x16x32_bf16 v[126:129], v[152:155], v[194:197], v[126:129]
	v_mfma_f32_16x16x32_bf16 v[122:125], v[170:173], v[194:197], v[122:125]
	v_mfma_f32_16x16x32_bf16 v[110:113], v[152:155], v[208:211], v[110:113]
	v_mfma_f32_16x16x32_bf16 v[106:109], v[170:173], v[208:211], v[106:109]
	v_mfma_f32_16x16x32_bf16 v[94:97], v[152:155], v[216:219], v[94:97]
	v_mfma_f32_16x16x32_bf16 v[90:93], v[170:173], v[216:219], v[90:93]
	v_mfma_f32_16x16x32_bf16 v[78:81], v[152:155], v[224:227], v[78:81]
	v_mfma_f32_16x16x32_bf16 v[74:77], v[170:173], v[224:227], v[74:77]
	v_mfma_f32_16x16x32_bf16 v[126:129], v[156:159], v[204:207], v[126:129]
	v_mfma_f32_16x16x32_bf16 v[122:125], v[174:177], v[204:207], v[122:125]
	v_mfma_f32_16x16x32_bf16 v[110:113], v[156:159], v[212:215], v[110:113]
	v_mfma_f32_16x16x32_bf16 v[106:109], v[174:177], v[212:215], v[106:109]
	v_mfma_f32_16x16x32_bf16 v[94:97], v[156:159], v[220:223], v[94:97]
	v_mfma_f32_16x16x32_bf16 v[90:93], v[174:177], v[220:223], v[90:93]
	v_mfma_f32_16x16x32_bf16 v[78:81], v[156:159], v[228:231], v[78:81]
	v_mfma_f32_16x16x32_bf16 v[74:77], v[174:177], v[228:231], v[74:77]
	s_setprio 0
	s_setprio 1
	v_mfma_f32_16x16x32_bf16 v[118:121], v[178:181], v[194:197], v[118:121]
	v_mfma_f32_16x16x32_bf16 v[114:117], v[186:189], v[194:197], v[114:117]
	v_mfma_f32_16x16x32_bf16 v[102:105], v[178:181], v[208:211], v[102:105]
	v_mfma_f32_16x16x32_bf16 v[98:101], v[186:189], v[208:211], v[98:101]
	v_mfma_f32_16x16x32_bf16 v[86:89], v[178:181], v[216:219], v[86:89]
	v_mfma_f32_16x16x32_bf16 v[82:85], v[186:189], v[216:219], v[82:85]
	v_mfma_f32_16x16x32_bf16 v[70:73], v[178:181], v[224:227], v[70:73]
	v_mfma_f32_16x16x32_bf16 v[66:69], v[186:189], v[224:227], v[66:69]
	v_mfma_f32_16x16x32_bf16 v[118:121], v[182:185], v[204:207], v[118:121]
	v_mfma_f32_16x16x32_bf16 v[114:117], v[190:193], v[204:207], v[114:117]
	v_mfma_f32_16x16x32_bf16 v[102:105], v[182:185], v[212:215], v[102:105]
	v_mfma_f32_16x16x32_bf16 v[98:101], v[190:193], v[212:215], v[98:101]
	v_mfma_f32_16x16x32_bf16 v[86:89], v[182:185], v[220:223], v[86:89]
	v_mfma_f32_16x16x32_bf16 v[82:85], v[190:193], v[220:223], v[82:85]
	v_mfma_f32_16x16x32_bf16 v[70:73], v[182:185], v[228:231], v[70:73]
	v_mfma_f32_16x16x32_bf16 v[66:69], v[190:193], v[228:231], v[66:69]
	s_setprio 0
	s_barrier
	s_add_i32 s34, s64, s36
	s_mov_b32 m0, s34
	ds_read_b128 v[194:197], v166 offset:49152
	ds_read_b128 v[204:207], v166 offset:50176
	ds_read_b128 v[208:211], v166 offset:51200
	ds_read_b128 v[212:215], v166 offset:52224
	ds_read_b128 v[216:219], v166 offset:53248
	ds_read_b128 v[220:223], v166 offset:54272
	ds_read_b128 v[224:227], v166 offset:55296
	ds_read_b128 v[228:231], v166 offset:56320
	global_load_lds_dwordx4 v134, s[66:67]
	s_add_i32 m0, s34, 0x2000
	s_add_u32 s30, s30, 0x80080
	s_addc_u32 s31, s31, 0
	s_add_i32 s34, s65, s36
	global_load_lds_dwordx4 v138, s[66:67]
	s_mov_b32 m0, s34
	s_nop 0
	global_load_lds_dwordx4 v134, s[30:31]
	s_add_i32 m0, s34, 0x2000
	s_nop 0
	global_load_lds_dwordx4 v138, s[30:31]
	s_mov_b32 m0, s79
	s_nop 0
	global_load_lds_dwordx4 v132, s[68:69]
	s_mov_b32 m0, s80
	s_nop 0
	global_load_lds_dwordx4 v136, s[68:69]
	s_waitcnt vmcnt(8)
	s_waitcnt lgkmcnt(0)
	s_barrier
	s_setprio 1
	s_waitcnt lgkmcnt(0)
	v_mfma_f32_16x16x32_bf16 v[62:65], v[152:155], v[194:197], v[62:65]
	v_mfma_f32_16x16x32_bf16 v[58:61], v[170:173], v[194:197], v[58:61]
	v_mfma_f32_16x16x32_bf16 v[46:49], v[152:155], v[208:211], v[46:49]
	v_mfma_f32_16x16x32_bf16 v[42:45], v[170:173], v[208:211], v[42:45]
	v_mfma_f32_16x16x32_bf16 v[30:33], v[152:155], v[216:219], v[30:33]
	v_mfma_f32_16x16x32_bf16 v[26:29], v[170:173], v[216:219], v[26:29]
	v_mfma_f32_16x16x32_bf16 v[14:17], v[152:155], v[224:227], v[14:17]
	v_mfma_f32_16x16x32_bf16 v[10:13], v[170:173], v[224:227], v[10:13]
	v_mfma_f32_16x16x32_bf16 v[62:65], v[156:159], v[204:207], v[62:65]
	v_mfma_f32_16x16x32_bf16 v[58:61], v[174:177], v[204:207], v[58:61]
	v_mfma_f32_16x16x32_bf16 v[46:49], v[156:159], v[212:215], v[46:49]
	v_mfma_f32_16x16x32_bf16 v[42:45], v[174:177], v[212:215], v[42:45]
	v_mfma_f32_16x16x32_bf16 v[30:33], v[156:159], v[220:223], v[30:33]
	v_mfma_f32_16x16x32_bf16 v[26:29], v[174:177], v[220:223], v[26:29]
	v_mfma_f32_16x16x32_bf16 v[14:17], v[156:159], v[228:231], v[14:17]
	v_mfma_f32_16x16x32_bf16 v[10:13], v[174:177], v[228:231], v[10:13]
	s_setprio 0
	s_setprio 1
	v_mfma_f32_16x16x32_bf16 v[54:57], v[178:181], v[194:197], v[54:57]
	v_mfma_f32_16x16x32_bf16 v[50:53], v[186:189], v[194:197], v[50:53]
	v_mfma_f32_16x16x32_bf16 v[38:41], v[178:181], v[208:211], v[38:41]
	v_mfma_f32_16x16x32_bf16 v[34:37], v[186:189], v[208:211], v[34:37]
	v_mfma_f32_16x16x32_bf16 v[22:25], v[178:181], v[216:219], v[22:25]
	v_mfma_f32_16x16x32_bf16 v[18:21], v[186:189], v[216:219], v[18:21]
	v_mfma_f32_16x16x32_bf16 v[6:9], v[178:181], v[224:227], v[6:9]
	v_mfma_f32_16x16x32_bf16 v[2:5], v[186:189], v[224:227], v[2:5]
	v_mfma_f32_16x16x32_bf16 v[54:57], v[182:185], v[204:207], v[54:57]
	v_mfma_f32_16x16x32_bf16 v[50:53], v[190:193], v[204:207], v[50:53]
	v_mfma_f32_16x16x32_bf16 v[38:41], v[182:185], v[212:215], v[38:41]
	v_mfma_f32_16x16x32_bf16 v[34:37], v[190:193], v[212:215], v[34:37]
	v_mfma_f32_16x16x32_bf16 v[22:25], v[182:185], v[220:223], v[22:25]
	v_mfma_f32_16x16x32_bf16 v[18:21], v[190:193], v[220:223], v[18:21]
	v_mfma_f32_16x16x32_bf16 v[6:9], v[182:185], v[228:231], v[6:9]
	v_mfma_f32_16x16x32_bf16 v[2:5], v[190:193], v[228:231], v[2:5]
	s_setprio 0
	s_barrier
	s_add_i32 s85, s85, 2
	s_add_u32 s28, s28, 0x100
	s_addc_u32 s29, s29, 0
	s_add_u32 s71, s71, 0x100
	s_addc_u32 s84, s84, 0
	s_cmp_gt_u32 s85, 29
	s_cbranch_scc0 .LBB0_765
	s_and_b64 vcc, exec, s[18:19]
	s_cbranch_vccz .LBB0_768
	s_barrier

; #define PG8_STAGE(bufoff, gbase, voff) do { _Pragma("unroll") for (int _i = 0; _i < 2; ++_i) \
;         __builtin_amdgcn_global_load_lds((const unsigned*)((const char*)(gbase) + (voff)[_i]), (PG8_LAS unsigned*)(lds + (bufoff) + ldsw + _i * 8192), 16, 0, 0); } while (0)
; #define PG8_LDA(dst, b, h) do { _Pragma("unroll") for (int m = 0; m < 4; ++m) _Pragma("unroll") for (int k = 0; k < 2; ++k) dst[m][k] = *(const PG8_LAS bf16x8*)(lds + PG8_SA(b, h) + aoff + m * 2048 + k * 1024); } while (0)
; #define PG8_LDB(dst, b, h) do { _Pragma("unroll") for (int n = 0; n < 2; ++n) _Pragma("unroll") for (int k = 0; k < 2; ++k) dst[n][k] = *(const PG8_LAS bf16x8*)(lds + PG8_SB(b, h) + boff + n * 2048 + k * 1024); } while (0)
; #define PG8_WAIT_V(n) asm volatile("s_waitcnt vmcnt(" #n ")" ::: "memory")
; template <class Epi, class Sched, bool ALIGN_EPI = false, bool SP2 = false>
; __device__ __forceinline__ void gemm_phase(PG8_LAS unsigned char* lds, const Gemm g, const Sched& S, const Epi& E) {
;     ...
;             const char* a1 = cA + (size_t)(t + 1) * kstep;
;             const char* a2 = last ? nA : cA + (size_t)(t + 2) * kstep; const char* b2 = last ? nB : cB + (size_t)(t + 2) * kstep;
;             const char* a3 = a2 + kstep; const char* b3 = b2 + kstep;
;             if (last && has_next) S.a_ready(nxt);
;             if constexpr (SP2) {
;             PG8_LDB(B0, 0, 0); PG8_LDB(B1, 0, 1); PG8_SCHED; PG8_LDA(At, 0, 0); PG8_STAGE(PG8_SA(1, 1), a1 + hstep, voffA);
;             PG8_WAIT_V(8); PG8_WAIT_L(0); PG8_BAR; PG8_MMA(0, 0, At, B0); PG8_MMA(0, 1, At, B1); PG8_BAR; PG8_SCHED;
;             PG8_LDA(At, 0, 1); PG8_STAGE(PG8_SB(0, 0), b2, voffB); PG8_STAGE(PG8_SB(0, 1), b2 + hstep, voffB); PG8_STAGE(PG8_SA(0, 0), a2, voffA);
;             PG8_WAIT_V(8); PG8_WAIT_L(0); PG8_BAR; PG8_MMA(1, 0, At, B0); PG8_MMA(1, 1, At, B1); PG8_BAR; PG8_SCHED;
;             PG8_LDB(B0, 1, 0); PG8_LDB(B1, 1, 1); PG8_SCHED; PG8_LDA(At, 1, 0); PG8_STAGE(PG8_SA(0, 1), a2 + hstep, voffA);
;             PG8_WAIT_V(8); PG8_WAIT_L(0); PG8_BAR; PG8_MMA(0, 0, At, B0); PG8_MMA(0, 1, At, B1); PG8_BAR; PG8_SCHED;
;             PG8_LDA(At, 1, 1); PG8_STAGE(PG8_SB(1, 0), b3, voffB); PG8_STAGE(PG8_SB(1, 1), b3 + hstep, voffB); PG8_STAGE(PG8_SA(1, 0), a3, voffA);
;             PG8_WAIT_V(8); PG8_WAIT_L(0); PG8_BAR; PG8_MMA(1, 0, At, B0); PG8_MMA(1, 1, At, B1); PG8_BAR; PG8_SCHED;
.LBB0_1177:
	ds_read_b128 v[146:149], v153
	ds_read_b128 v[158:161], v153 offset:1024
	ds_read_b128 v[162:165], v153 offset:2048
	ds_read_b128 v[166:169], v153 offset:3072
	ds_read_b128 v[170:173], v154
	ds_read_b128 v[174:177], v154 offset:1024
	ds_read_b128 v[178:181], v154 offset:2048
	ds_read_b128 v[182:185], v154 offset:3072
	s_add_u32 s26, s24, 0xfff80080
	s_addc_u32 s27, s25, -1
	s_cmp_eq_u32 s65, 28
	s_cselect_b32 s29, s19, s27
	s_cselect_b32 s28, s57, s26
	s_cselect_b32 s27, s17, s64
	s_cselect_b32 s26, s58, s59
	s_add_i32 m0, s39, 0xc000
	ds_read_b128 v[186:189], v155
	ds_read_b128 v[190:193], v155 offset:1024
	ds_read_b128 v[194:197], v155 offset:2048
	ds_read_b128 v[202:205], v155 offset:3072
	ds_read_b128 v[206:209], v155 offset:4096
	ds_read_b128 v[210:213], v155 offset:5120
	ds_read_b128 v[214:217], v155 offset:6144
	ds_read_b128 v[218:221], v155 offset:7168
	global_load_lds_dwordx4 v138, s[24:25]
	s_add_i32 m0, s39, 0xe000
	s_nop 0
	global_load_lds_dwordx4 v140, s[24:25]
	s_waitcnt vmcnt(8)
	s_waitcnt lgkmcnt(0)
	s_barrier
	s_setprio 1
	s_waitcnt lgkmcnt(0)
	v_mfma_f32_16x16x32_bf16 v[126:129], v[146:149], v[186:189], v[126:129]
	v_mfma_f32_16x16x32_bf16 v[122:125], v[162:165], v[186:189], v[122:125]
	v_mfma_f32_16x16x32_bf16 v[110:113], v[146:149], v[194:197], v[110:113]
	v_mfma_f32_16x16x32_bf16 v[106:109], v[162:165], v[194:197], v[106:109]
	v_mfma_f32_16x16x32_bf16 v[94:97], v[146:149], v[206:209], v[94:97]
	v_mfma_f32_16x16x32_bf16 v[90:93], v[162:165], v[206:209], v[90:93]
	v_mfma_f32_16x16x32_bf16 v[78:81], v[146:149], v[214:217], v[78:81]
	v_mfma_f32_16x16x32_bf16 v[74:77], v[162:165], v[214:217], v[74:77]
	v_mfma_f32_16x16x32_bf16 v[126:129], v[158:161], v[190:193], v[126:129]
	v_mfma_f32_16x16x32_bf16 v[122:125], v[166:169], v[190:193], v[122:125]
	v_mfma_f32_16x16x32_bf16 v[110:113], v[158:161], v[202:205], v[110:113]
	v_mfma_f32_16x16x32_bf16 v[106:109], v[166:169], v[202:205], v[106:109]
	v_mfma_f32_16x16x32_bf16 v[94:97], v[158:161], v[210:213], v[94:97]
	v_mfma_f32_16x16x32_bf16 v[90:93], v[166:169], v[210:213], v[90:93]
	v_mfma_f32_16x16x32_bf16 v[78:81], v[158:161], v[218:221], v[78:81]
	v_mfma_f32_16x16x32_bf16 v[74:77], v[166:169], v[218:221], v[74:77]
	s_setprio 0
	s_setprio 1
	v_mfma_f32_16x16x32_bf16 v[118:121], v[170:173], v[186:189], v[118:121]
	v_mfma_f32_16x16x32_bf16 v[114:117], v[178:181], v[186:189], v[114:117]
	v_mfma_f32_16x16x32_bf16 v[102:105], v[170:173], v[194:197], v[102:105]
	v_mfma_f32_16x16x32_bf16 v[98:101], v[178:181], v[194:197], v[98:101]
	v_mfma_f32_16x16x32_bf16 v[86:89], v[170:173], v[206:209], v[86:89]
	v_mfma_f32_16x16x32_bf16 v[82:85], v[178:181], v[206:209], v[82:85]
	v_mfma_f32_16x16x32_bf16 v[70:73], v[170:173], v[214:217], v[70:73]
	v_mfma_f32_16x16x32_bf16 v[66:69], v[178:181], v[214:217], v[66:69]
	v_mfma_f32_16x16x32_bf16 v[118:121], v[174:177], v[190:193], v[118:121]
	v_mfma_f32_16x16x32_bf16 v[114:117], v[182:185], v[190:193], v[114:117]
	v_mfma_f32_16x16x32_bf16 v[102:105], v[174:177], v[202:205], v[102:105]
	v_mfma_f32_16x16x32_bf16 v[98:101], v[182:185], v[202:205], v[98:101]
	v_mfma_f32_16x16x32_bf16 v[86:89], v[174:177], v[210:213], v[86:89]
	v_mfma_f32_16x16x32_bf16 v[82:85], v[182:185], v[210:213], v[82:85]
	v_mfma_f32_16x16x32_bf16 v[70:73], v[174:177], v[218:221], v[70:73]
	v_mfma_f32_16x16x32_bf16 v[66:69], v[182:185], v[218:221], v[66:69]
	s_setprio 0
	s_barrier
	s_add_i32 s66, s53, s38
	s_add_u32 s70, s26, 0x80
	s_addc_u32 s71, s27, 0
	s_mov_b32 m0, s66
	ds_read_b128 v[186:189], v155 offset:16384
	ds_read_b128 v[190:193], v155 offset:17408
	ds_read_b128 v[194:197], v155 offset:18432
	ds_read_b128 v[202:205], v155 offset:19456
	ds_read_b128 v[206:209], v155 offset:20480
	ds_read_b128 v[210:213], v155 offset:21504
	ds_read_b128 v[214:217], v155 offset:22528
	ds_read_b128 v[218:221], v155 offset:23552
	global_load_lds_dwordx4 v132, s[26:27]
	s_add_i32 m0, s66, 0x2000
	s_add_u32 s66, s26, 0x80000
	s_addc_u32 s67, s27, 0
	s_add_i32 s68, s54, s38
	global_load_lds_dwordx4 v136, s[26:27]
	s_mov_b32 m0, s68
	s_add_u32 s74, s28, 0x80
	s_addc_u32 s75, s29, 0
	global_load_lds_dwordx4 v132, s[66:67]
	s_add_i32 m0, s68, 0x2000
	s_nop 0
	global_load_lds_dwordx4 v136, s[66:67]
	s_mov_b32 m0, s39
	s_nop 0
	global_load_lds_dwordx4 v130, s[28:29]
	s_mov_b32 m0, s40
	s_nop 0
	global_load_lds_dwordx4 v134, s[28:29]
	s_waitcnt vmcnt(8)
	s_waitcnt lgkmcnt(0)
	s_barrier
	s_setprio 1
	s_waitcnt lgkmcnt(0)
	v_mfma_f32_16x16x32_bf16 v[62:65], v[146:149], v[186:189], v[62:65]
	v_mfma_f32_16x16x32_bf16 v[58:61], v[162:165], v[186:189], v[58:61]
	v_mfma_f32_16x16x32_bf16 v[46:49], v[146:149], v[194:197], v[46:49]
	v_mfma_f32_16x16x32_bf16 v[42:45], v[162:165], v[194:197], v[42:45]
	v_mfma_f32_16x16x32_bf16 v[30:33], v[146:149], v[206:209], v[30:33]
	v_mfma_f32_16x16x32_bf16 v[26:29], v[162:165], v[206:209], v[26:29]
	v_mfma_f32_16x16x32_bf16 v[14:17], v[146:149], v[214:217], v[14:17]
	v_mfma_f32_16x16x32_bf16 v[10:13], v[162:165], v[214:217], v[10:13]
	v_mfma_f32_16x16x32_bf16 v[62:65], v[158:161], v[190:193], v[62:65]
	v_mfma_f32_16x16x32_bf16 v[58:61], v[166:169], v[190:193], v[58:61]
	v_mfma_f32_16x16x32_bf16 v[46:49], v[158:161], v[202:205], v[46:49]
	v_mfma_f32_16x16x32_bf16 v[42:45], v[166:169], v[202:205], v[42:45]
	v_mfma_f32_16x16x32_bf16 v[30:33], v[158:161], v[210:213], v[30:33]
	v_mfma_f32_16x16x32_bf16 v[26:29], v[166:169], v[210:213], v[26:29]
	v_mfma_f32_16x16x32_bf16 v[14:17], v[158:161], v[218:221], v[14:17]
	v_mfma_f32_16x16x32_bf16 v[10:13], v[166:169], v[218:221], v[10:13]
	s_setprio 0
	s_setprio 1
	v_mfma_f32_16x16x32_bf16 v[54:57], v[170:173], v[186:189], v[54:57]
	v_mfma_f32_16x16x32_bf16 v[50:53], v[178:181], v[186:189], v[50:53]
	v_mfma_f32_16x16x32_bf16 v[38:41], v[170:173], v[194:197], v[38:41]
	v_mfma_f32_16x16x32_bf16 v[34:37], v[178:181], v[194:197], v[34:37]
	v_mfma_f32_16x16x32_bf16 v[22:25], v[170:173], v[206:209], v[22:25]
	v_mfma_f32_16x16x32_bf16 v[18:21], v[178:181], v[206:209], v[18:21]
	v_mfma_f32_16x16x32_bf16 v[6:9], v[170:173], v[214:217], v[6:9]
	v_mfma_f32_16x16x32_bf16 v[2:5], v[178:181], v[214:217], v[2:5]
	v_mfma_f32_16x16x32_bf16 v[54:57], v[174:177], v[190:193], v[54:57]
	v_mfma_f32_16x16x32_bf16 v[50:53], v[182:185], v[190:193], v[50:53]
	v_mfma_f32_16x16x32_bf16 v[38:41], v[174:177], v[202:205], v[38:41]
	v_mfma_f32_16x16x32_bf16 v[34:37], v[182:185], v[202:205], v[34:37]
	v_mfma_f32_16x16x32_bf16 v[22:25], v[174:177], v[210:213], v[22:25]
	v_mfma_f32_16x16x32_bf16 v[18:21], v[182:185], v[210:213], v[18:21]
	v_mfma_f32_16x16x32_bf16 v[6:9], v[174:177], v[218:221], v[6:9]
	v_mfma_f32_16x16x32_bf16 v[2:5], v[182:185], v[218:221], v[2:5]
	s_setprio 0
	s_barrier
; #define PG8_STAGE(bufoff, gbase, voff) do { _Pragma("unroll") for (int _i = 0; _i < 2; ++_i) \
;         __builtin_amdgcn_global_load_lds((const unsigned*)((const char*)(gbase) + (voff)[_i]), (PG8_LAS unsigned*)(lds + (bufoff) + ldsw + _i * 8192), 16, 0, 0); } while (0)
; #define PG8_LDA(dst, b, h) do { _Pragma("unroll") for (int m = 0; m < 4; ++m) _Pragma("unroll") for (int k = 0; k < 2; ++k) dst[m][k] = *(const PG8_LAS bf16x8*)(lds + PG8_SA(b, h) + aoff + m * 2048 + k * 1024); } while (0)
; #define PG8_LDB(dst, b, h) do { _Pragma("unroll") for (int n = 0; n < 2; ++n) _Pragma("unroll") for (int k = 0; k < 2; ++k) dst[n][k] = *(const PG8_LAS bf16x8*)(lds + PG8_SB(b, h) + boff + n * 2048 + k * 1024); } while (0)
; #define PG8_MMA(ai, bj, At, Bt) do { __builtin_amdgcn_s_setprio(1); _Pragma("unroll") for (int m = 0; m < 4; ++m) _Pragma("unroll") for (int n = 0; n < 2; ++n) _Pragma("unroll") for (int k = 0; k < 2; ++k) \
;         acc[ai][bj][m][n] = __builtin_amdgcn_mfma_f32_16x16x32_bf16(Bt[n][k], At[m][k], acc[ai][bj][m][n], 0, 0, 0); __builtin_amdgcn_s_setprio(0); } while (0)
; #define PG8_WAIT_V(n) asm volatile("s_waitcnt vmcnt(" #n ")" ::: "memory")
; #define PG8_WAIT_L(n) asm volatile("s_waitcnt lgkmcnt(" #n ")" ::: "memory")
; template <class Epi, class Sched, bool ALIGN_EPI = false, bool SP2 = false>
; __device__ __forceinline__ void gemm_phase(PG8_LAS unsigned char* lds, const Gemm g, const Sched& S, const Epi& E) {
;     ...
;         for (int t = 0; t < nt; t += 2) {
;             const bool last = (t == nt - 2);
;             const char* a1 = cA + (size_t)(t + 1) * kstep;
;             const char* a2 = last ? nA : cA + (size_t)(t + 2) * kstep; const char* b2 = last ? nB : cB + (size_t)(t + 2) * kstep;
;             const char* a3 = a2 + kstep; const char* b3 = b2 + kstep;
;             if (last && has_next) S.a_ready(nxt);
;     ...
;             PG8_LDB(B0, 1, 0); PG8_LDB(B1, 1, 1); PG8_SCHED; PG8_LDA(At, 1, 0); PG8_STAGE(PG8_SA(0, 1), a2 + hstep, voffA);
;             PG8_WAIT_V(8); PG8_WAIT_L(0); PG8_BAR; PG8_MMA(0, 0, At, B0); PG8_MMA(0, 1, At, B1); PG8_BAR; PG8_SCHED;
;             PG8_LDA(At, 1, 1); PG8_STAGE(PG8_SB(1, 0), b3, voffB); PG8_STAGE(PG8_SB(1, 1), b3 + hstep, voffB); PG8_STAGE(PG8_SA(1, 0), a3, voffA);
;             PG8_WAIT_V(8); PG8_WAIT_L(0); PG8_BAR; PG8_MMA(1, 0, At, B0); PG8_MMA(1, 1, At, B1); PG8_BAR; PG8_SCHED;
	s_add_i32 s66, 0, 0x18000
	v_add_u32_e32 v157, s66, v151
	s_add_i32 s67, 0, 0x1c000
	ds_read_b128 v[146:149], v157
	ds_read_b128 v[158:161], v157 offset:1024
	ds_read_b128 v[162:165], v157 offset:2048
	ds_read_b128 v[166:169], v157 offset:3072
	v_add_u32_e32 v157, s67, v151
	ds_read_b128 v[170:173], v157
	ds_read_b128 v[174:177], v157 offset:1024
	ds_read_b128 v[178:181], v157 offset:2048
	ds_read_b128 v[182:185], v157 offset:3072
	s_add_u32 s28, s28, 0x80000
	s_addc_u32 s29, s29, 0
	s_mov_b32 m0, s41
	ds_read_b128 v[186:189], v155 offset:32768
	ds_read_b128 v[190:193], v155 offset:33792
	ds_read_b128 v[194:197], v155 offset:34816
	ds_read_b128 v[202:205], v155 offset:35840
	ds_read_b128 v[206:209], v155 offset:36864
	ds_read_b128 v[210:213], v155 offset:37888
	ds_read_b128 v[214:217], v155 offset:38912
	ds_read_b128 v[218:221], v155 offset:39936
	global_load_lds_dwordx4 v130, s[28:29]
	s_mov_b32 m0, s42
	s_nop 0
	global_load_lds_dwordx4 v134, s[28:29]
	s_waitcnt vmcnt(8)
	s_waitcnt lgkmcnt(0)
	s_barrier
	s_setprio 1
	s_waitcnt lgkmcnt(0)
	v_mfma_f32_16x16x32_bf16 v[126:129], v[146:149], v[186:189], v[126:129]
	v_mfma_f32_16x16x32_bf16 v[122:125], v[162:165], v[186:189], v[122:125]
	v_mfma_f32_16x16x32_bf16 v[110:113], v[146:149], v[194:197], v[110:113]
	v_mfma_f32_16x16x32_bf16 v[106:109], v[162:165], v[194:197], v[106:109]
	v_mfma_f32_16x16x32_bf16 v[94:97], v[146:149], v[206:209], v[94:97]
	v_mfma_f32_16x16x32_bf16 v[90:93], v[162:165], v[206:209], v[90:93]
	v_mfma_f32_16x16x32_bf16 v[78:81], v[146:149], v[214:217], v[78:81]
	v_mfma_f32_16x16x32_bf16 v[74:77], v[162:165], v[214:217], v[74:77]
	v_mfma_f32_16x16x32_bf16 v[126:129], v[158:161], v[190:193], v[126:129]
	v_mfma_f32_16x16x32_bf16 v[122:125], v[166:169], v[190:193], v[122:125]
	v_mfma_f32_16x16x32_bf16 v[110:113], v[158:161], v[202:205], v[110:113]
	v_mfma_f32_16x16x32_bf16 v[106:109], v[166:169], v[202:205], v[106:109]
	v_mfma_f32_16x16x32_bf16 v[94:97], v[158:161], v[210:213], v[94:97]
	v_mfma_f32_16x16x32_bf16 v[90:93], v[166:169], v[210:213], v[90:93]
	v_mfma_f32_16x16x32_bf16 v[78:81], v[158:161], v[218:221], v[78:81]
	v_mfma_f32_16x16x32_bf16 v[74:77], v[166:169], v[218:221], v[74:77]
	s_setprio 0
	s_setprio 1
	v_mfma_f32_16x16x32_bf16 v[118:121], v[170:173], v[186:189], v[118:121]
	v_mfma_f32_16x16x32_bf16 v[114:117], v[178:181], v[186:189], v[114:117]
	v_mfma_f32_16x16x32_bf16 v[102:105], v[170:173], v[194:197], v[102:105]
	v_mfma_f32_16x16x32_bf16 v[98:101], v[178:181], v[194:197], v[98:101]
	v_mfma_f32_16x16x32_bf16 v[86:89], v[170:173], v[206:209], v[86:89]
	v_mfma_f32_16x16x32_bf16 v[82:85], v[178:181], v[206:209], v[82:85]
	v_mfma_f32_16x16x32_bf16 v[70:73], v[170:173], v[214:217], v[70:73]
	v_mfma_f32_16x16x32_bf16 v[66:69], v[178:181], v[214:217], v[66:69]
	v_mfma_f32_16x16x32_bf16 v[118:121], v[174:177], v[190:193], v[118:121]
	v_mfma_f32_16x16x32_bf16 v[114:117], v[182:185], v[190:193], v[114:117]
	v_mfma_f32_16x16x32_bf16 v[102:105], v[174:177], v[202:205], v[102:105]
	v_mfma_f32_16x16x32_bf16 v[98:101], v[182:185], v[202:205], v[98:101]
	v_mfma_f32_16x16x32_bf16 v[86:89], v[174:177], v[210:213], v[86:89]
	v_mfma_f32_16x16x32_bf16 v[82:85], v[182:185], v[210:213], v[82:85]
	v_mfma_f32_16x16x32_bf16 v[70:73], v[174:177], v[218:221], v[70:73]
	v_mfma_f32_16x16x32_bf16 v[66:69], v[182:185], v[218:221], v[66:69]
	s_setprio 0
	s_barrier
	s_add_i32 s28, s66, s38
	s_mov_b32 m0, s28
	ds_read_b128 v[186:189], v155 offset:49152
	ds_read_b128 v[190:193], v155 offset:50176
	ds_read_b128 v[194:197], v155 offset:51200
	ds_read_b128 v[202:205], v155 offset:52224
	ds_read_b128 v[206:209], v155 offset:53248
	ds_read_b128 v[210:213], v155 offset:54272
	ds_read_b128 v[214:217], v155 offset:55296
	ds_read_b128 v[218:221], v155 offset:56320
	global_load_lds_dwordx4 v132, s[70:71]
	s_add_i32 m0, s28, 0x2000
	s_add_u32 s26, s26, 0x80080
	s_addc_u32 s27, s27, 0
	s_add_i32 s28, s67, s38
	global_load_lds_dwordx4 v136, s[70:71]
	s_mov_b32 m0, s28
	s_nop 0
	global_load_lds_dwordx4 v132, s[26:27]
	s_add_i32 m0, s28, 0x2000
	s_nop 0
	global_load_lds_dwordx4 v136, s[26:27]
	s_mov_b32 m0, s45
	s_nop 0
	global_load_lds_dwordx4 v130, s[74:75]
	s_mov_b32 m0, s52
	s_nop 0
	global_load_lds_dwordx4 v134, s[74:75]
	s_waitcnt vmcnt(8)
	s_waitcnt lgkmcnt(0)
	s_barrier
	s_setprio 1
	s_waitcnt lgkmcnt(0)
	v_mfma_f32_16x16x32_bf16 v[62:65], v[146:149], v[186:189], v[62:65]
	v_mfma_f32_16x16x32_bf16 v[58:61], v[162:165], v[186:189], v[58:61]
	v_mfma_f32_16x16x32_bf16 v[46:49], v[146:149], v[194:197], v[46:49]
	v_mfma_f32_16x16x32_bf16 v[42:45], v[162:165], v[194:197], v[42:45]
	v_mfma_f32_16x16x32_bf16 v[30:33], v[146:149], v[206:209], v[30:33]
	v_mfma_f32_16x16x32_bf16 v[26:29], v[162:165], v[206:209], v[26:29]
	v_mfma_f32_16x16x32_bf16 v[14:17], v[146:149], v[214:217], v[14:17]
	v_mfma_f32_16x16x32_bf16 v[10:13], v[162:165], v[214:217], v[10:13]
	v_mfma_f32_16x16x32_bf16 v[62:65], v[158:161], v[190:193], v[62:65]
	v_mfma_f32_16x16x32_bf16 v[58:61], v[166:169], v[190:193], v[58:61]
	v_mfma_f32_16x16x32_bf16 v[46:49], v[158:161], v[202:205], v[46:49]
	v_mfma_f32_16x16x32_bf16 v[42:45], v[166:169], v[202:205], v[42:45]
	v_mfma_f32_16x16x32_bf16 v[30:33], v[158:161], v[210:213], v[30:33]
	v_mfma_f32_16x16x32_bf16 v[26:29], v[166:169], v[210:213], v[26:29]
	v_mfma_f32_16x16x32_bf16 v[14:17], v[158:161], v[218:221], v[14:17]
	v_mfma_f32_16x16x32_bf16 v[10:13], v[166:169], v[218:221], v[10:13]
	s_setprio 0
	s_setprio 1
	v_mfma_f32_16x16x32_bf16 v[54:57], v[170:173], v[186:189], v[54:57]
	v_mfma_f32_16x16x32_bf16 v[50:53], v[178:181], v[186:189], v[50:53]
	v_mfma_f32_16x16x32_bf16 v[38:41], v[170:173], v[194:197], v[38:41]
	v_mfma_f32_16x16x32_bf16 v[34:37], v[178:181], v[194:197], v[34:37]
	v_mfma_f32_16x16x32_bf16 v[22:25], v[170:173], v[206:209], v[22:25]
	v_mfma_f32_16x16x32_bf16 v[18:21], v[178:181], v[206:209], v[18:21]
	v_mfma_f32_16x16x32_bf16 v[6:9], v[170:173], v[214:217], v[6:9]
	v_mfma_f32_16x16x32_bf16 v[2:5], v[178:181], v[214:217], v[2:5]
	v_mfma_f32_16x16x32_bf16 v[54:57], v[174:177], v[190:193], v[54:57]
	v_mfma_f32_16x16x32_bf16 v[50:53], v[182:185], v[190:193], v[50:53]
	v_mfma_f32_16x16x32_bf16 v[38:41], v[174:177], v[202:205], v[38:41]
	v_mfma_f32_16x16x32_bf16 v[34:37], v[182:185], v[202:205], v[34:37]
	v_mfma_f32_16x16x32_bf16 v[22:25], v[174:177], v[210:213], v[22:25]
	v_mfma_f32_16x16x32_bf16 v[18:21], v[182:185], v[210:213], v[18:21]
	v_mfma_f32_16x16x32_bf16 v[6:9], v[174:177], v[218:221], v[6:9]
	v_mfma_f32_16x16x32_bf16 v[2:5], v[182:185], v[218:221], v[2:5]
	s_setprio 0
	s_barrier
	s_add_i32 s65, s65, 2
	s_add_u32 s24, s24, 0x100
	s_addc_u32 s25, s25, 0
	s_add_u32 s59, s59, 0x100
	s_addc_u32 s64, s64, 0
	s_cmp_gt_u32 s65, 29
	s_cbranch_scc0 .LBB0_1177
	s_and_b64 vcc, exec, s[14:15]
	s_cbranch_vccz .LBB0_1180
	s_barrier
